# P5 gated merge carried in f32 accumulators across the 4 segments (acc *= g_n/g_n+1 at boundaries, one bf16 pack/store at the end) instead of bf16 gy read-modify-write per segment; + B/C/A/M nop cleanu
# speedup vs baseline: 1.0165x; 1.0165x over previous
.LBB0_788:
	s_ashr_i32 s2, s8, 3
	s_add_i32 s2, s9, s2
	s_ashr_i32 s3, s2, 31
	s_lshr_b32 s3, s3, 27
	s_add_i32 s3, s2, s3
	s_ashr_i32 s8, s3, 5
	s_lshl_b32 s9, s8, 3
	s_sub_i32 s8, 64, s9
	s_min_i32 s10, s8, 8
	s_abs_i32 s8, s10
	v_cvt_f32_u32_e32 v250, s8
	s_sub_i32 s14, 0, s8
	s_andn2_b32 s3, s3, 31
	s_sub_i32 s2, s2, s3
	v_rcp_iflag_f32_e32 v250, v250
	s_abs_i32 s3, s2
	s_xor_b32 s11, s2, s10
	s_and_b32 s44, s37, 3
	v_mul_f32_e32 v250, 0x4f7ffffe, v250
	v_cvt_u32_f32_e32 v250, v250
	s_ashr_i32 s11, s11, 31
	v_readfirstlane_b32 s15, v250
	s_mul_i32 s14, s14, s15
	s_mul_hi_u32 s14, s15, s14
	s_add_i32 s15, s15, s14
	s_mul_hi_u32 s14, s3, s15
	s_mul_i32 s15, s14, s8
	s_sub_i32 s3, s3, s15
	s_add_i32 s16, s14, 1
	s_sub_i32 s15, s3, s8
	s_cmp_ge_u32 s3, s8
	s_cselect_b32 s14, s16, s14
	s_cselect_b32 s3, s15, s3
	s_add_i32 s15, s14, 1
	s_cmp_ge_u32 s3, s8
	s_cselect_b32 s3, s15, s14
	s_xor_b32 s3, s3, s11
	s_sub_i32 s8, s3, s11
	s_mul_i32 s3, s8, s10
	s_sub_i32 s2, s2, s3
	s_add_i32 s14, s9, s2
	s_lshl_b32 s2, s44, 24
	s_add_u32 s10, s20, s2
	s_addc_u32 s11, s21, 0
	s_lshl_b32 s2, s44, 20
	s_add_u32 s16, s26, s2
	s_addc_u32 s17, s28, 0
.LBB0_789:
	s_ashr_i32 s15, s14, 31
	s_lshl_b64 s[2:3], s[14:15], 18
	s_add_u32 s18, s10, s2
	s_addc_u32 s19, s11, s3
	s_and_b64 s[2:3], s[42:43], exec
	s_cselect_b32 s2, s19, s1
	s_cselect_b32 s3, s18, s0
	s_ashr_i32 s9, s8, 31
	s_lshl_b64 s[24:25], s[8:9], 18
	s_add_u32 s38, s16, s24
	s_addc_u32 s39, s17, s25
	s_and_b64 s[24:25], s[42:43], exec
	s_cselect_b32 s9, s39, s23
	s_cselect_b32 s15, s38, s22
	s_add_u32 s0, s0, 0x20080
	s_addc_u32 s1, s1, 0
	s_add_u32 s48, s22, 0x100
	s_addc_u32 s49, s23, 0
	s_mov_b32 s50, -2
	s_cmp_lg_u32 s45, 0
	s_cbranch_scc1 .Lm_keepacc
	v_mov_b32_e32 v2, 0
	v_mov_b32_e32 v3, v2
	v_mov_b32_e32 v4, v2
	v_mov_b32_e32 v5, v2
	v_mov_b32_e32 v6, v2
	v_mov_b32_e32 v7, v2
	v_mov_b32_e32 v8, v2
	v_mov_b32_e32 v9, v2
	v_mov_b32_e32 v10, v2
	v_mov_b32_e32 v11, v2
	v_mov_b32_e32 v12, v2
	v_mov_b32_e32 v13, v2
	v_mov_b32_e32 v14, v2
	v_mov_b32_e32 v15, v2
	v_mov_b32_e32 v16, v2
	v_mov_b32_e32 v17, v2
	v_mov_b32_e32 v18, v2
	v_mov_b32_e32 v19, v2
	v_mov_b32_e32 v20, v2
	v_mov_b32_e32 v21, v2
	v_mov_b32_e32 v22, v2
	v_mov_b32_e32 v23, v2
	v_mov_b32_e32 v24, v2
	v_mov_b32_e32 v25, v2
	v_mov_b32_e32 v26, v2
	v_mov_b32_e32 v27, v2
	v_mov_b32_e32 v28, v2
	v_mov_b32_e32 v29, v2
	v_mov_b32_e32 v30, v2
	v_mov_b32_e32 v31, v2
	v_mov_b32_e32 v32, v2
	v_mov_b32_e32 v33, v2
	v_mov_b32_e32 v34, v2
	v_mov_b32_e32 v35, v2
	v_mov_b32_e32 v36, v2
	v_mov_b32_e32 v37, v2
	v_mov_b32_e32 v38, v2
	v_mov_b32_e32 v39, v2
	v_mov_b32_e32 v40, v2
	v_mov_b32_e32 v41, v2
	v_mov_b32_e32 v42, v2
	v_mov_b32_e32 v43, v2
	v_mov_b32_e32 v44, v2
	v_mov_b32_e32 v45, v2
	v_mov_b32_e32 v46, v2
	v_mov_b32_e32 v47, v2
	v_mov_b32_e32 v48, v2
	v_mov_b32_e32 v49, v2
	v_mov_b32_e32 v50, v2
	v_mov_b32_e32 v51, v2
	v_mov_b32_e32 v52, v2
	v_mov_b32_e32 v53, v2
	v_mov_b32_e32 v54, v2
	v_mov_b32_e32 v55, v2
	v_mov_b32_e32 v56, v2
	v_mov_b32_e32 v57, v2
	v_mov_b32_e32 v58, v2
	v_mov_b32_e32 v59, v2
	v_mov_b32_e32 v60, v2
	v_mov_b32_e32 v61, v2
	v_mov_b32_e32 v62, v2
	v_mov_b32_e32 v63, v2
	v_mov_b32_e32 v64, v2
	v_mov_b32_e32 v65, v2
	v_mov_b32_e32 v66, v2
	v_mov_b32_e32 v67, v2
	v_mov_b32_e32 v68, v2
	v_mov_b32_e32 v69, v2
	v_mov_b32_e32 v70, v2
	v_mov_b32_e32 v71, v2
	v_mov_b32_e32 v72, v2
	v_mov_b32_e32 v73, v2
	v_mov_b32_e32 v74, v2
	v_mov_b32_e32 v75, v2
	v_mov_b32_e32 v76, v2
	v_mov_b32_e32 v77, v2
	v_mov_b32_e32 v78, v2
	v_mov_b32_e32 v79, v2
	v_mov_b32_e32 v80, v2
	v_mov_b32_e32 v81, v2
	v_mov_b32_e32 v82, v2
	v_mov_b32_e32 v83, v2
	v_mov_b32_e32 v84, v2
	v_mov_b32_e32 v85, v2
	v_mov_b32_e32 v86, v2
	v_mov_b32_e32 v87, v2
	v_mov_b32_e32 v88, v2
	v_mov_b32_e32 v89, v2
	v_mov_b32_e32 v90, v2
	v_mov_b32_e32 v91, v2
	v_mov_b32_e32 v92, v2
	v_mov_b32_e32 v93, v2
	v_mov_b32_e32 v94, v2
	v_mov_b32_e32 v95, v2
	v_mov_b32_e32 v96, v2
	v_mov_b32_e32 v97, v2
	v_mov_b32_e32 v98, v2
	v_mov_b32_e32 v99, v2
	v_mov_b32_e32 v100, v2
	v_mov_b32_e32 v101, v2
	v_mov_b32_e32 v102, v2
	v_mov_b32_e32 v103, v2
	v_mov_b32_e32 v104, v2
	v_mov_b32_e32 v105, v2
	v_mov_b32_e32 v106, v2
	v_mov_b32_e32 v107, v2
	v_mov_b32_e32 v108, v2
	v_mov_b32_e32 v109, v2
	v_mov_b32_e32 v110, v2
	v_mov_b32_e32 v111, v2
	v_mov_b32_e32 v112, v2
	v_mov_b32_e32 v113, v2
	v_mov_b32_e32 v114, v2
	v_mov_b32_e32 v115, v2
	v_mov_b32_e32 v116, v2
	v_mov_b32_e32 v117, v2
	v_mov_b32_e32 v118, v2
	v_mov_b32_e32 v119, v2
	v_mov_b32_e32 v120, v2
	v_mov_b32_e32 v121, v2
	v_mov_b32_e32 v122, v2
	v_mov_b32_e32 v123, v2
	v_mov_b32_e32 v124, v2
	v_mov_b32_e32 v125, v2
	v_mov_b32_e32 v126, v2
	v_mov_b32_e32 v127, v2
	v_mov_b32_e32 v128, v2
	v_mov_b32_e32 v129, v2
.Lm_keepacc:
.LBB0_790:
	s_add_u32 s22, s0, 0xfffe0080
	s_addc_u32 s23, s1, -1
	s_add_i32 s51, 0, 0x10000
	s_cmp_eq_u32 s50, 4
	s_cselect_b32 s25, s2, s23
	s_cselect_b32 s24, s3, s22
	s_cselect_b32 s23, s9, s49
	s_cselect_b32 s22, s15, s48
	s_add_i32 s54, 0, 0x14000
	v_add_u32_e32 v142, s51, v196
	v_add_u32_e32 v168, s54, v196
	ds_read_b128 v[130:133], v142
	ds_read_b128 v[134:137], v142 offset:1024
	ds_read_b128 v[138:141], v142 offset:2048
	ds_read_b128 v[142:145], v142 offset:3072
	ds_read_b128 v[146:149], v168
	ds_read_b128 v[150:153], v168 offset:1024
	ds_read_b128 v[164:167], v168 offset:2048
	ds_read_b128 v[168:171], v168 offset:3072
	v_lshl_add_u64 v[192:193], s[0:1], 0, v[160:161]
	s_add_i32 m0, s29, 0xc000
	ds_read_b128 v[172:175], v197
	ds_read_b128 v[180:183], v197 offset:1024
	ds_read_b128 v[184:187], v197 offset:2048
	ds_read_b128 v[188:191], v197 offset:3072
	ds_read_b128 v[198:201], v197 offset:4096
	ds_read_b128 v[212:215], v197 offset:5120
	ds_read_b128 v[216:219], v197 offset:6144
	ds_read_b128 v[220:223], v197 offset:7168
	global_load_lds_dwordx4 v[192:193], off
	v_lshl_add_u64 v[192:193], s[0:1], 0, v[162:163]
	s_add_i32 m0, s29, 0xe000
	s_nop 0
	global_load_lds_dwordx4 v[192:193], off
	s_waitcnt vmcnt(8)
	s_waitcnt lgkmcnt(0)
	s_barrier
	s_setprio 3
	s_waitcnt lgkmcnt(0)
	v_mfma_f32_16x16x32_bf16 v[126:129], v[130:133], v[172:175], v[126:129]
	v_mfma_f32_16x16x32_bf16 v[122:125], v[138:141], v[172:175], v[122:125]
	v_mfma_f32_16x16x32_bf16 v[118:121], v[130:133], v[184:187], v[118:121]
	v_mfma_f32_16x16x32_bf16 v[110:113], v[138:141], v[184:187], v[110:113]
	v_mfma_f32_16x16x32_bf16 v[94:97], v[130:133], v[198:201], v[94:97]
	v_mfma_f32_16x16x32_bf16 v[90:93], v[138:141], v[198:201], v[90:93]
	v_mfma_f32_16x16x32_bf16 v[86:89], v[130:133], v[216:219], v[86:89]
	v_mfma_f32_16x16x32_bf16 v[78:81], v[138:141], v[216:219], v[78:81]
	v_mfma_f32_16x16x32_bf16 v[126:129], v[134:137], v[180:183], v[126:129]
	v_mfma_f32_16x16x32_bf16 v[122:125], v[142:145], v[180:183], v[122:125]
	v_mfma_f32_16x16x32_bf16 v[118:121], v[134:137], v[188:191], v[118:121]
	v_mfma_f32_16x16x32_bf16 v[110:113], v[142:145], v[188:191], v[110:113]
	v_mfma_f32_16x16x32_bf16 v[94:97], v[134:137], v[212:215], v[94:97]
	v_mfma_f32_16x16x32_bf16 v[90:93], v[142:145], v[212:215], v[90:93]
	v_mfma_f32_16x16x32_bf16 v[86:89], v[134:137], v[220:223], v[86:89]
	v_mfma_f32_16x16x32_bf16 v[78:81], v[142:145], v[220:223], v[78:81]
	s_setprio 0
	s_setprio 3
	v_mfma_f32_16x16x32_bf16 v[114:117], v[146:149], v[172:175], v[114:117]
	v_mfma_f32_16x16x32_bf16 v[106:109], v[164:167], v[172:175], v[106:109]
	v_mfma_f32_16x16x32_bf16 v[102:105], v[146:149], v[184:187], v[102:105]
	v_mfma_f32_16x16x32_bf16 v[98:101], v[164:167], v[184:187], v[98:101]
	v_mfma_f32_16x16x32_bf16 v[82:85], v[146:149], v[198:201], v[82:85]
	v_mfma_f32_16x16x32_bf16 v[74:77], v[164:167], v[198:201], v[74:77]
	v_mfma_f32_16x16x32_bf16 v[70:73], v[146:149], v[216:219], v[70:73]
	v_mfma_f32_16x16x32_bf16 v[66:69], v[164:167], v[216:219], v[66:69]
	v_mfma_f32_16x16x32_bf16 v[114:117], v[150:153], v[180:183], v[114:117]
	v_mfma_f32_16x16x32_bf16 v[106:109], v[168:171], v[180:183], v[106:109]
	v_mfma_f32_16x16x32_bf16 v[102:105], v[150:153], v[188:191], v[102:105]
	v_mfma_f32_16x16x32_bf16 v[98:101], v[168:171], v[188:191], v[98:101]
	v_mfma_f32_16x16x32_bf16 v[82:85], v[150:153], v[212:215], v[82:85]
	v_mfma_f32_16x16x32_bf16 v[74:77], v[168:171], v[212:215], v[74:77]
	v_mfma_f32_16x16x32_bf16 v[70:73], v[150:153], v[220:223], v[70:73]
	v_mfma_f32_16x16x32_bf16 v[66:69], v[168:171], v[220:223], v[66:69]
	s_setprio 0
	s_barrier
	s_add_i32 s51, s51, s33
	v_lshl_add_u64 v[192:193], s[22:23], 0, v[0:1]
	s_mov_b32 m0, s51
	ds_read_b128 v[172:175], v197 offset:16384
	ds_read_b128 v[180:183], v197 offset:17408
	ds_read_b128 v[184:187], v197 offset:18432
	ds_read_b128 v[188:191], v197 offset:19456
	ds_read_b128 v[198:201], v197 offset:20480
	ds_read_b128 v[212:215], v197 offset:21504
	ds_read_b128 v[216:219], v197 offset:22528
	ds_read_b128 v[220:223], v197 offset:23552
	global_load_lds_dwordx4 v[192:193], off
	s_add_i32 m0, s51, 0x2000
	s_add_u32 s52, s22, 0x20000
	v_lshl_add_u64 v[202:203], s[22:23], 0, v[154:155]
	s_addc_u32 s53, s23, 0
	s_add_i32 s51, s54, s33
	global_load_lds_dwordx4 v[202:203], off
	v_lshl_add_u64 v[224:225], s[52:53], 0, v[0:1]
	s_mov_b32 m0, s51
	v_lshl_add_u64 v[226:227], s[24:25], 0, v[156:157]
	global_load_lds_dwordx4 v[224:225], off
	v_lshl_add_u64 v[224:225], s[52:53], 0, v[154:155]
	s_add_i32 m0, s51, 0x2000
	s_nop 0
	global_load_lds_dwordx4 v[224:225], off
	v_lshl_add_u64 v[224:225], s[24:25], 0, v[158:159]
	s_mov_b32 m0, s29
	s_nop 0
	global_load_lds_dwordx4 v[224:225], off
	s_mov_b32 m0, s30
	s_nop 0
	global_load_lds_dwordx4 v[226:227], off
	s_waitcnt vmcnt(8)
	s_waitcnt lgkmcnt(0)
	s_barrier
	s_setprio 3
	s_waitcnt lgkmcnt(0)
	v_mfma_f32_16x16x32_bf16 v[62:65], v[130:133], v[172:175], v[62:65]
	v_mfma_f32_16x16x32_bf16 v[58:61], v[138:141], v[172:175], v[58:61]
	v_mfma_f32_16x16x32_bf16 v[54:57], v[130:133], v[184:187], v[54:57]
	v_mfma_f32_16x16x32_bf16 v[46:49], v[138:141], v[184:187], v[46:49]
	v_mfma_f32_16x16x32_bf16 v[30:33], v[130:133], v[198:201], v[30:33]
	v_mfma_f32_16x16x32_bf16 v[26:29], v[138:141], v[198:201], v[26:29]
	v_mfma_f32_16x16x32_bf16 v[22:25], v[130:133], v[216:219], v[22:25]
	v_mfma_f32_16x16x32_bf16 v[14:17], v[138:141], v[216:219], v[14:17]
	v_mfma_f32_16x16x32_bf16 v[62:65], v[134:137], v[180:183], v[62:65]
	v_mfma_f32_16x16x32_bf16 v[58:61], v[142:145], v[180:183], v[58:61]
	v_mfma_f32_16x16x32_bf16 v[54:57], v[134:137], v[188:191], v[54:57]
	v_mfma_f32_16x16x32_bf16 v[46:49], v[142:145], v[188:191], v[46:49]
	v_mfma_f32_16x16x32_bf16 v[30:33], v[134:137], v[212:215], v[30:33]
	v_mfma_f32_16x16x32_bf16 v[26:29], v[142:145], v[212:215], v[26:29]
	v_mfma_f32_16x16x32_bf16 v[22:25], v[134:137], v[220:223], v[22:25]
	v_mfma_f32_16x16x32_bf16 v[14:17], v[142:145], v[220:223], v[14:17]
	s_setprio 0
	s_setprio 3
	v_mfma_f32_16x16x32_bf16 v[50:53], v[146:149], v[172:175], v[50:53]
	v_mfma_f32_16x16x32_bf16 v[42:45], v[164:167], v[172:175], v[42:45]
	v_mfma_f32_16x16x32_bf16 v[38:41], v[146:149], v[184:187], v[38:41]
	v_mfma_f32_16x16x32_bf16 v[34:37], v[164:167], v[184:187], v[34:37]
	v_mfma_f32_16x16x32_bf16 v[18:21], v[146:149], v[198:201], v[18:21]
	v_mfma_f32_16x16x32_bf16 v[10:13], v[164:167], v[198:201], v[10:13]
	v_mfma_f32_16x16x32_bf16 v[6:9], v[146:149], v[216:219], v[6:9]
	v_mfma_f32_16x16x32_bf16 v[2:5], v[164:167], v[216:219], v[2:5]
	v_mfma_f32_16x16x32_bf16 v[50:53], v[150:153], v[180:183], v[50:53]
	v_mfma_f32_16x16x32_bf16 v[42:45], v[168:171], v[180:183], v[42:45]
	v_mfma_f32_16x16x32_bf16 v[38:41], v[150:153], v[188:191], v[38:41]
	v_mfma_f32_16x16x32_bf16 v[34:37], v[168:171], v[188:191], v[34:37]
	v_mfma_f32_16x16x32_bf16 v[18:21], v[150:153], v[212:215], v[18:21]
	v_mfma_f32_16x16x32_bf16 v[10:13], v[168:171], v[212:215], v[10:13]
	v_mfma_f32_16x16x32_bf16 v[6:9], v[150:153], v[220:223], v[6:9]
	v_mfma_f32_16x16x32_bf16 v[2:5], v[168:171], v[220:223], v[2:5]
	s_setprio 0
	s_barrier
	s_add_i32 s51, 0, 0x18000
	s_add_i32 s52, 0, 0x1c000
	v_add_u32_e32 v142, s51, v196
	v_add_u32_e32 v168, s52, v196
	ds_read_b128 v[130:133], v142
	ds_read_b128 v[134:137], v142 offset:1024
	ds_read_b128 v[138:141], v142 offset:2048
	ds_read_b128 v[142:145], v142 offset:3072
	ds_read_b128 v[146:149], v168
	ds_read_b128 v[150:153], v168 offset:1024
	ds_read_b128 v[164:167], v168 offset:2048
	ds_read_b128 v[168:171], v168 offset:3072
	s_add_u32 s24, s24, 0x20000
	s_addc_u32 s25, s25, 0
	s_mov_b32 m0, s31
	v_lshl_add_u64 v[228:229], s[24:25], 0, v[158:159]
	ds_read_b128 v[172:175], v197 offset:32768
	ds_read_b128 v[180:183], v197 offset:33792
	ds_read_b128 v[184:187], v197 offset:34816
	ds_read_b128 v[188:191], v197 offset:35840
	ds_read_b128 v[198:201], v197 offset:36864
	ds_read_b128 v[212:215], v197 offset:37888
	ds_read_b128 v[216:219], v197 offset:38912
	ds_read_b128 v[220:223], v197 offset:39936
	global_load_lds_dwordx4 v[228:229], off
	v_lshl_add_u64 v[228:229], s[24:25], 0, v[156:157]
	s_mov_b32 m0, s34
	s_nop 0
	global_load_lds_dwordx4 v[228:229], off
	s_waitcnt vmcnt(8)
	s_waitcnt lgkmcnt(0)
	s_barrier
	s_setprio 3
	s_waitcnt lgkmcnt(0)
	v_mfma_f32_16x16x32_bf16 v[126:129], v[130:133], v[172:175], v[126:129]
	v_mfma_f32_16x16x32_bf16 v[122:125], v[138:141], v[172:175], v[122:125]
	v_mfma_f32_16x16x32_bf16 v[118:121], v[130:133], v[184:187], v[118:121]
	v_mfma_f32_16x16x32_bf16 v[110:113], v[138:141], v[184:187], v[110:113]
	v_mfma_f32_16x16x32_bf16 v[94:97], v[130:133], v[198:201], v[94:97]
	v_mfma_f32_16x16x32_bf16 v[90:93], v[138:141], v[198:201], v[90:93]
	v_mfma_f32_16x16x32_bf16 v[86:89], v[130:133], v[216:219], v[86:89]
	v_mfma_f32_16x16x32_bf16 v[78:81], v[138:141], v[216:219], v[78:81]
	v_mfma_f32_16x16x32_bf16 v[126:129], v[134:137], v[180:183], v[126:129]
	v_mfma_f32_16x16x32_bf16 v[122:125], v[142:145], v[180:183], v[122:125]
	v_mfma_f32_16x16x32_bf16 v[118:121], v[134:137], v[188:191], v[118:121]
	v_mfma_f32_16x16x32_bf16 v[110:113], v[142:145], v[188:191], v[110:113]
	v_mfma_f32_16x16x32_bf16 v[94:97], v[134:137], v[212:215], v[94:97]
	v_mfma_f32_16x16x32_bf16 v[90:93], v[142:145], v[212:215], v[90:93]
	v_mfma_f32_16x16x32_bf16 v[86:89], v[134:137], v[220:223], v[86:89]
	v_mfma_f32_16x16x32_bf16 v[78:81], v[142:145], v[220:223], v[78:81]
	s_setprio 0
	s_setprio 3
	v_mfma_f32_16x16x32_bf16 v[114:117], v[146:149], v[172:175], v[114:117]
	v_mfma_f32_16x16x32_bf16 v[106:109], v[164:167], v[172:175], v[106:109]
	v_mfma_f32_16x16x32_bf16 v[102:105], v[146:149], v[184:187], v[102:105]
	v_mfma_f32_16x16x32_bf16 v[98:101], v[164:167], v[184:187], v[98:101]
	v_mfma_f32_16x16x32_bf16 v[82:85], v[146:149], v[198:201], v[82:85]
	v_mfma_f32_16x16x32_bf16 v[74:77], v[164:167], v[198:201], v[74:77]
	v_mfma_f32_16x16x32_bf16 v[70:73], v[146:149], v[216:219], v[70:73]
	v_mfma_f32_16x16x32_bf16 v[66:69], v[164:167], v[216:219], v[66:69]
	v_mfma_f32_16x16x32_bf16 v[114:117], v[150:153], v[180:183], v[114:117]
	v_mfma_f32_16x16x32_bf16 v[106:109], v[168:171], v[180:183], v[106:109]
	v_mfma_f32_16x16x32_bf16 v[102:105], v[150:153], v[188:191], v[102:105]
	v_mfma_f32_16x16x32_bf16 v[98:101], v[168:171], v[188:191], v[98:101]
	v_mfma_f32_16x16x32_bf16 v[82:85], v[150:153], v[212:215], v[82:85]
	v_mfma_f32_16x16x32_bf16 v[74:77], v[168:171], v[212:215], v[74:77]
	v_mfma_f32_16x16x32_bf16 v[70:73], v[150:153], v[220:223], v[70:73]
	v_mfma_f32_16x16x32_bf16 v[66:69], v[168:171], v[220:223], v[66:69]
	s_setprio 0
	s_barrier
	s_add_i32 s24, s51, s33
	v_lshl_add_u64 v[192:193], v[192:193], 0, s[12:13]
	s_mov_b32 m0, s24
	ds_read_b128 v[172:175], v197 offset:49152
	ds_read_b128 v[180:183], v197 offset:50176
	ds_read_b128 v[184:187], v197 offset:51200
	ds_read_b128 v[188:191], v197 offset:52224
	ds_read_b128 v[198:201], v197 offset:53248
	ds_read_b128 v[212:215], v197 offset:54272
	ds_read_b128 v[216:219], v197 offset:55296
	ds_read_b128 v[220:223], v197 offset:56320
	global_load_lds_dwordx4 v[192:193], off
	s_add_i32 m0, s24, 0x2000
	s_add_u32 s22, s22, 0x20080
	v_lshl_add_u64 v[192:193], v[202:203], 0, s[12:13]
	s_addc_u32 s23, s23, 0
	s_add_i32 s24, s52, s33
	global_load_lds_dwordx4 v[192:193], off
	v_lshl_add_u64 v[192:193], s[22:23], 0, v[0:1]
	s_mov_b32 m0, s24
	s_nop 0
	global_load_lds_dwordx4 v[192:193], off
	v_lshl_add_u64 v[192:193], s[22:23], 0, v[154:155]
	s_add_i32 m0, s24, 0x2000
	s_nop 0
	global_load_lds_dwordx4 v[192:193], off
	v_lshl_add_u64 v[192:193], v[224:225], 0, s[12:13]
	s_mov_b32 m0, s35
	s_nop 0
	global_load_lds_dwordx4 v[192:193], off
	v_lshl_add_u64 v[192:193], v[226:227], 0, s[12:13]
	s_mov_b32 m0, s36
	s_nop 0
	global_load_lds_dwordx4 v[192:193], off
	s_waitcnt vmcnt(8)
	s_waitcnt lgkmcnt(0)
	s_barrier
	s_setprio 3
	s_waitcnt lgkmcnt(0)
	v_mfma_f32_16x16x32_bf16 v[62:65], v[130:133], v[172:175], v[62:65]
	v_mfma_f32_16x16x32_bf16 v[58:61], v[138:141], v[172:175], v[58:61]
	v_mfma_f32_16x16x32_bf16 v[54:57], v[130:133], v[184:187], v[54:57]
	v_mfma_f32_16x16x32_bf16 v[46:49], v[138:141], v[184:187], v[46:49]
	v_mfma_f32_16x16x32_bf16 v[30:33], v[130:133], v[198:201], v[30:33]
	v_mfma_f32_16x16x32_bf16 v[26:29], v[138:141], v[198:201], v[26:29]
	v_mfma_f32_16x16x32_bf16 v[22:25], v[130:133], v[216:219], v[22:25]
	v_mfma_f32_16x16x32_bf16 v[14:17], v[138:141], v[216:219], v[14:17]
	v_mfma_f32_16x16x32_bf16 v[62:65], v[134:137], v[180:183], v[62:65]
	v_mfma_f32_16x16x32_bf16 v[58:61], v[142:145], v[180:183], v[58:61]
	v_mfma_f32_16x16x32_bf16 v[54:57], v[134:137], v[188:191], v[54:57]
	v_mfma_f32_16x16x32_bf16 v[46:49], v[142:145], v[188:191], v[46:49]
	v_mfma_f32_16x16x32_bf16 v[30:33], v[134:137], v[212:215], v[30:33]
	v_mfma_f32_16x16x32_bf16 v[26:29], v[142:145], v[212:215], v[26:29]
	v_mfma_f32_16x16x32_bf16 v[22:25], v[134:137], v[220:223], v[22:25]
	v_mfma_f32_16x16x32_bf16 v[14:17], v[142:145], v[220:223], v[14:17]
	s_setprio 0
	s_setprio 3
	v_mfma_f32_16x16x32_bf16 v[50:53], v[146:149], v[172:175], v[50:53]
	v_mfma_f32_16x16x32_bf16 v[42:45], v[164:167], v[172:175], v[42:45]
	v_mfma_f32_16x16x32_bf16 v[38:41], v[146:149], v[184:187], v[38:41]
	v_mfma_f32_16x16x32_bf16 v[34:37], v[164:167], v[184:187], v[34:37]
	v_mfma_f32_16x16x32_bf16 v[18:21], v[146:149], v[198:201], v[18:21]
	v_mfma_f32_16x16x32_bf16 v[10:13], v[164:167], v[198:201], v[10:13]
	v_mfma_f32_16x16x32_bf16 v[6:9], v[146:149], v[216:219], v[6:9]
	v_mfma_f32_16x16x32_bf16 v[2:5], v[164:167], v[216:219], v[2:5]
	v_mfma_f32_16x16x32_bf16 v[50:53], v[150:153], v[180:183], v[50:53]
	v_mfma_f32_16x16x32_bf16 v[42:45], v[168:171], v[180:183], v[42:45]
	v_mfma_f32_16x16x32_bf16 v[38:41], v[150:153], v[188:191], v[38:41]
	v_mfma_f32_16x16x32_bf16 v[34:37], v[168:171], v[188:191], v[34:37]
	v_mfma_f32_16x16x32_bf16 v[18:21], v[150:153], v[212:215], v[18:21]
	v_mfma_f32_16x16x32_bf16 v[10:13], v[168:171], v[212:215], v[10:13]
	v_mfma_f32_16x16x32_bf16 v[6:9], v[150:153], v[220:223], v[6:9]
	v_mfma_f32_16x16x32_bf16 v[2:5], v[168:171], v[220:223], v[2:5]
	s_setprio 0
	s_barrier
	s_add_i32 s50, s50, 2
	s_add_u32 s0, s0, 0x100
	s_addc_u32 s1, s1, 0
	s_add_u32 s48, s48, 0x100
	s_addc_u32 s49, s49, 0
	s_cmp_gt_u32 s50, 5
	s_cbranch_scc0 .LBB0_790
	v_readlane_b32 s0, v254, 6
	v_readlane_b32 s1, v254, 7
	s_and_b64 vcc, exec, s[0:1]
	s_cbranch_vccz .LBB0_793
	s_barrier
.LBB0_793:
	s_lshl_b32 s2, s47, 8
	v_readlane_b32 s3, v253, 62
	s_add_i32 s2, s2, s3
	v_add_u32_e32 v250, s2, v194
	s_lshl_b32 s2, s46, 8
	v_readlane_b32 s3, v254, 18
	s_or_b32 s2, s2, s3
	v_lshl_add_u32 v251, v195, 3, s2
	v_lshlrev_b32_e32 v251, 1, v251
	v_lshl_add_u32 v248, v250, 13, v251
	v_lshl_add_u32 v249, v250, 11, v251
	s_lshl_b32 s0, s45, 11
	s_add_u32 s0, s4, s0
	s_addc_u32 s1, s5, 0
	s_mov_b64 s[56:57], s[0:1]
	s_mov_b64 s[82:83], s[6:7]
	s_add_u32 s58, s0, 0x20000
	s_addc_u32 s59, s1, 0
	s_add_u32 s84, s6, 0x8000
	s_addc_u32 s85, s7, 0
	s_add_u32 s60, s0, 0x40000
	s_addc_u32 s61, s1, 0
	s_add_u32 s86, s6, 0x10000
	s_addc_u32 s87, s7, 0
	s_add_u32 s62, s0, 0x60000
	s_addc_u32 s63, s1, 0
	s_add_u32 s88, s6, 0x18000
	s_addc_u32 s89, s7, 0
	s_add_u32 s64, s0, 0x100000
	s_addc_u32 s65, s1, 0
	s_add_u32 s90, s6, 0x40000
	s_addc_u32 s91, s7, 0
	s_add_u32 s66, s0, 0x120000
	s_addc_u32 s67, s1, 0
	s_add_u32 s92, s6, 0x48000
	s_addc_u32 s93, s7, 0
	s_add_u32 s68, s0, 0x140000
	s_addc_u32 s69, s1, 0
	s_add_u32 s94, s6, 0x50000
	s_addc_u32 s95, s7, 0
	s_add_u32 s70, s0, 0x160000
	s_addc_u32 s71, s1, 0
	s_add_u32 s96, s6, 0x58000
	s_addc_u32 s97, s7, 0
	s_cmp_eq_u32 s45, 3
	s_cbranch_scc1 .Lm_final
	global_load_dwordx4 v[130:133], v248, s[56:57]
	global_load_dwordx4 v[134:137], v248, s[56:57] offset:2048
	global_load_dwordx4 v[138:141], v248, s[56:57] offset:256
	global_load_dwordx4 v[142:145], v248, s[56:57] offset:2304
	global_load_dwordx4 v[146:149], v248, s[58:59]
	global_load_dwordx4 v[150:153], v248, s[58:59] offset:2048
	global_load_dwordx4 v[164:167], v248, s[58:59] offset:256
	global_load_dwordx4 v[168:171], v248, s[58:59] offset:2304
	global_load_dwordx4 v[172:175], v248, s[60:61]
	global_load_dwordx4 v[180:183], v248, s[60:61] offset:2048
	global_load_dwordx4 v[184:187], v248, s[60:61] offset:256
	global_load_dwordx4 v[188:191], v248, s[60:61] offset:2304
	global_load_dwordx4 v[198:201], v248, s[62:63]
	global_load_dwordx4 v[212:215], v248, s[62:63] offset:2048
	global_load_dwordx4 v[216:219], v248, s[62:63] offset:256
	global_load_dwordx4 v[220:223], v248, s[62:63] offset:2304
	global_load_dwordx4 v[224:227], v248, s[64:65]
	global_load_dwordx4 v[228:231], v248, s[64:65] offset:2048
	global_load_dwordx4 v[232:235], v248, s[64:65] offset:256
	global_load_dwordx4 v[236:239], v248, s[64:65] offset:2304
	global_load_dwordx4 v[240:243], v248, s[66:67]
	global_load_dwordx4 v[244:247], v248, s[66:67] offset:2048
	s_waitcnt vmcnt(20)
	v_lshlrev_b32_e32 v250, 16, v134
	v_and_b32_e32 v251, 0xffff0000, v134
	v_lshlrev_b32_e32 v192, 16, v130
	v_and_b32_e32 v193, 0xffff0000, v130
	v_max_f32_e32 v250, 0x0da24260, v250
	v_max_f32_e32 v251, 0x0da24260, v251
	v_rcp_f32_e32 v250, v250
	v_rcp_f32_e32 v251, v251
	v_max_f32_e32 v192, 0x0da24260, v192
	v_max_f32_e32 v193, 0x0da24260, v193
	v_mul_f32_e32 v250, v250, v192
	v_mul_f32_e32 v251, v251, v193
	v_mul_f32_e32 v126, v126, v250
	v_mul_f32_e32 v127, v127, v251
	v_lshlrev_b32_e32 v250, 16, v135
	v_and_b32_e32 v251, 0xffff0000, v135
	v_lshlrev_b32_e32 v192, 16, v131
	v_and_b32_e32 v193, 0xffff0000, v131
	v_max_f32_e32 v250, 0x0da24260, v250
	v_max_f32_e32 v251, 0x0da24260, v251
	v_rcp_f32_e32 v250, v250
	v_rcp_f32_e32 v251, v251
	v_max_f32_e32 v192, 0x0da24260, v192
	v_max_f32_e32 v193, 0x0da24260, v193
	v_mul_f32_e32 v250, v250, v192
	v_mul_f32_e32 v251, v251, v193
	v_mul_f32_e32 v128, v128, v250
	v_mul_f32_e32 v129, v129, v251
	v_lshlrev_b32_e32 v250, 16, v136
	v_and_b32_e32 v251, 0xffff0000, v136
	v_lshlrev_b32_e32 v192, 16, v132
	v_and_b32_e32 v193, 0xffff0000, v132
	v_max_f32_e32 v250, 0x0da24260, v250
	v_max_f32_e32 v251, 0x0da24260, v251
	v_rcp_f32_e32 v250, v250
	v_rcp_f32_e32 v251, v251
	v_max_f32_e32 v192, 0x0da24260, v192
	v_max_f32_e32 v193, 0x0da24260, v193
	v_mul_f32_e32 v250, v250, v192
	v_mul_f32_e32 v251, v251, v193
	v_mul_f32_e32 v122, v122, v250
	v_mul_f32_e32 v123, v123, v251
	v_lshlrev_b32_e32 v250, 16, v137
	v_and_b32_e32 v251, 0xffff0000, v137
	v_lshlrev_b32_e32 v192, 16, v133
	v_and_b32_e32 v193, 0xffff0000, v133
	v_max_f32_e32 v250, 0x0da24260, v250
	v_max_f32_e32 v251, 0x0da24260, v251
	v_rcp_f32_e32 v250, v250
	v_rcp_f32_e32 v251, v251
	v_max_f32_e32 v192, 0x0da24260, v192
	v_max_f32_e32 v193, 0x0da24260, v193
	v_mul_f32_e32 v250, v250, v192
	v_mul_f32_e32 v251, v251, v193
	v_mul_f32_e32 v124, v124, v250
	v_mul_f32_e32 v125, v125, v251
	global_load_dwordx4 v[130:133], v248, s[66:67] offset:256
	global_load_dwordx4 v[134:137], v248, s[66:67] offset:2304
	s_waitcnt vmcnt(20)
	v_lshlrev_b32_e32 v250, 16, v142
	v_and_b32_e32 v251, 0xffff0000, v142
	v_lshlrev_b32_e32 v192, 16, v138
	v_and_b32_e32 v193, 0xffff0000, v138
	v_max_f32_e32 v250, 0x0da24260, v250
	v_max_f32_e32 v251, 0x0da24260, v251
	v_rcp_f32_e32 v250, v250
	v_rcp_f32_e32 v251, v251
	v_max_f32_e32 v192, 0x0da24260, v192
	v_max_f32_e32 v193, 0x0da24260, v193
	v_mul_f32_e32 v250, v250, v192
	v_mul_f32_e32 v251, v251, v193
	v_mul_f32_e32 v114, v114, v250
	v_mul_f32_e32 v115, v115, v251
	v_lshlrev_b32_e32 v250, 16, v143
	v_and_b32_e32 v251, 0xffff0000, v143
	v_lshlrev_b32_e32 v192, 16, v139
	v_and_b32_e32 v193, 0xffff0000, v139
	v_max_f32_e32 v250, 0x0da24260, v250
	v_max_f32_e32 v251, 0x0da24260, v251
	v_rcp_f32_e32 v250, v250
	v_rcp_f32_e32 v251, v251
	v_max_f32_e32 v192, 0x0da24260, v192
	v_max_f32_e32 v193, 0x0da24260, v193
	v_mul_f32_e32 v250, v250, v192
	v_mul_f32_e32 v251, v251, v193
	v_mul_f32_e32 v116, v116, v250
	v_mul_f32_e32 v117, v117, v251
	v_lshlrev_b32_e32 v250, 16, v144
	v_and_b32_e32 v251, 0xffff0000, v144
	v_lshlrev_b32_e32 v192, 16, v140
	v_and_b32_e32 v193, 0xffff0000, v140
	v_max_f32_e32 v250, 0x0da24260, v250
	v_max_f32_e32 v251, 0x0da24260, v251
	v_rcp_f32_e32 v250, v250
	v_rcp_f32_e32 v251, v251
	v_max_f32_e32 v192, 0x0da24260, v192
	v_max_f32_e32 v193, 0x0da24260, v193
	v_mul_f32_e32 v250, v250, v192
	v_mul_f32_e32 v251, v251, v193
	v_mul_f32_e32 v106, v106, v250
	v_mul_f32_e32 v107, v107, v251
	v_lshlrev_b32_e32 v250, 16, v145
	v_and_b32_e32 v251, 0xffff0000, v145
	v_lshlrev_b32_e32 v192, 16, v141
	v_and_b32_e32 v193, 0xffff0000, v141
	v_max_f32_e32 v250, 0x0da24260, v250
	v_max_f32_e32 v251, 0x0da24260, v251
	v_rcp_f32_e32 v250, v250
	v_rcp_f32_e32 v251, v251
	v_max_f32_e32 v192, 0x0da24260, v192
	v_max_f32_e32 v193, 0x0da24260, v193
	v_mul_f32_e32 v250, v250, v192
	v_mul_f32_e32 v251, v251, v193
	v_mul_f32_e32 v108, v108, v250
	v_mul_f32_e32 v109, v109, v251
	global_load_dwordx4 v[138:141], v248, s[68:69]
	global_load_dwordx4 v[142:145], v248, s[68:69] offset:2048
	s_waitcnt vmcnt(20)
	v_lshlrev_b32_e32 v250, 16, v150
	v_and_b32_e32 v251, 0xffff0000, v150
	v_lshlrev_b32_e32 v192, 16, v146
	v_and_b32_e32 v193, 0xffff0000, v146
	v_max_f32_e32 v250, 0x0da24260, v250
	v_max_f32_e32 v251, 0x0da24260, v251
	v_rcp_f32_e32 v250, v250
	v_rcp_f32_e32 v251, v251
	v_max_f32_e32 v192, 0x0da24260, v192
	v_max_f32_e32 v193, 0x0da24260, v193
	v_mul_f32_e32 v250, v250, v192
	v_mul_f32_e32 v251, v251, v193
	v_mul_f32_e32 v118, v118, v250
	v_mul_f32_e32 v119, v119, v251
	v_lshlrev_b32_e32 v250, 16, v151
	v_and_b32_e32 v251, 0xffff0000, v151
	v_lshlrev_b32_e32 v192, 16, v147
	v_and_b32_e32 v193, 0xffff0000, v147
	v_max_f32_e32 v250, 0x0da24260, v250
	v_max_f32_e32 v251, 0x0da24260, v251
	v_rcp_f32_e32 v250, v250
	v_rcp_f32_e32 v251, v251
	v_max_f32_e32 v192, 0x0da24260, v192
	v_max_f32_e32 v193, 0x0da24260, v193
	v_mul_f32_e32 v250, v250, v192
	v_mul_f32_e32 v251, v251, v193
	v_mul_f32_e32 v120, v120, v250
	v_mul_f32_e32 v121, v121, v251
	v_lshlrev_b32_e32 v250, 16, v152
	v_and_b32_e32 v251, 0xffff0000, v152
	v_lshlrev_b32_e32 v192, 16, v148
	v_and_b32_e32 v193, 0xffff0000, v148
	v_max_f32_e32 v250, 0x0da24260, v250
	v_max_f32_e32 v251, 0x0da24260, v251
	v_rcp_f32_e32 v250, v250
	v_rcp_f32_e32 v251, v251
	v_max_f32_e32 v192, 0x0da24260, v192
	v_max_f32_e32 v193, 0x0da24260, v193
	v_mul_f32_e32 v250, v250, v192
	v_mul_f32_e32 v251, v251, v193
	v_mul_f32_e32 v110, v110, v250
	v_mul_f32_e32 v111, v111, v251
	v_lshlrev_b32_e32 v250, 16, v153
	v_and_b32_e32 v251, 0xffff0000, v153
	v_lshlrev_b32_e32 v192, 16, v149
	v_and_b32_e32 v193, 0xffff0000, v149
	v_max_f32_e32 v250, 0x0da24260, v250
	v_max_f32_e32 v251, 0x0da24260, v251
	v_rcp_f32_e32 v250, v250
	v_rcp_f32_e32 v251, v251
	v_max_f32_e32 v192, 0x0da24260, v192
	v_max_f32_e32 v193, 0x0da24260, v193
	v_mul_f32_e32 v250, v250, v192
	v_mul_f32_e32 v251, v251, v193
	v_mul_f32_e32 v112, v112, v250
	v_mul_f32_e32 v113, v113, v251
	global_load_dwordx4 v[146:149], v248, s[68:69] offset:256
	global_load_dwordx4 v[150:153], v248, s[68:69] offset:2304
	s_waitcnt vmcnt(20)
	v_lshlrev_b32_e32 v250, 16, v168
	v_and_b32_e32 v251, 0xffff0000, v168
	v_lshlrev_b32_e32 v192, 16, v164
	v_and_b32_e32 v193, 0xffff0000, v164
	v_max_f32_e32 v250, 0x0da24260, v250
	v_max_f32_e32 v251, 0x0da24260, v251
	v_rcp_f32_e32 v250, v250
	v_rcp_f32_e32 v251, v251
	v_max_f32_e32 v192, 0x0da24260, v192
	v_max_f32_e32 v193, 0x0da24260, v193
	v_mul_f32_e32 v250, v250, v192
	v_mul_f32_e32 v251, v251, v193
	v_mul_f32_e32 v102, v102, v250
	v_mul_f32_e32 v103, v103, v251
	v_lshlrev_b32_e32 v250, 16, v169
	v_and_b32_e32 v251, 0xffff0000, v169
	v_lshlrev_b32_e32 v192, 16, v165
	v_and_b32_e32 v193, 0xffff0000, v165
	v_max_f32_e32 v250, 0x0da24260, v250
	v_max_f32_e32 v251, 0x0da24260, v251
	v_rcp_f32_e32 v250, v250
	v_rcp_f32_e32 v251, v251
	v_max_f32_e32 v192, 0x0da24260, v192
	v_max_f32_e32 v193, 0x0da24260, v193
	v_mul_f32_e32 v250, v250, v192
	v_mul_f32_e32 v251, v251, v193
	v_mul_f32_e32 v104, v104, v250
	v_mul_f32_e32 v105, v105, v251
	v_lshlrev_b32_e32 v250, 16, v170
	v_and_b32_e32 v251, 0xffff0000, v170
	v_lshlrev_b32_e32 v192, 16, v166
	v_and_b32_e32 v193, 0xffff0000, v166
	v_max_f32_e32 v250, 0x0da24260, v250
	v_max_f32_e32 v251, 0x0da24260, v251
	v_rcp_f32_e32 v250, v250
	v_rcp_f32_e32 v251, v251
	v_max_f32_e32 v192, 0x0da24260, v192
	v_max_f32_e32 v193, 0x0da24260, v193
	v_mul_f32_e32 v250, v250, v192
	v_mul_f32_e32 v251, v251, v193
	v_mul_f32_e32 v98, v98, v250
	v_mul_f32_e32 v99, v99, v251
	v_lshlrev_b32_e32 v250, 16, v171
	v_and_b32_e32 v251, 0xffff0000, v171
	v_lshlrev_b32_e32 v192, 16, v167
	v_and_b32_e32 v193, 0xffff0000, v167
	v_max_f32_e32 v250, 0x0da24260, v250
	v_max_f32_e32 v251, 0x0da24260, v251
	v_rcp_f32_e32 v250, v250
	v_rcp_f32_e32 v251, v251
	v_max_f32_e32 v192, 0x0da24260, v192
	v_max_f32_e32 v193, 0x0da24260, v193
	v_mul_f32_e32 v250, v250, v192
	v_mul_f32_e32 v251, v251, v193
	v_mul_f32_e32 v100, v100, v250
	v_mul_f32_e32 v101, v101, v251
	global_load_dwordx4 v[164:167], v248, s[70:71]
	global_load_dwordx4 v[168:171], v248, s[70:71] offset:2048
	s_waitcnt vmcnt(20)
	v_lshlrev_b32_e32 v250, 16, v180
	v_and_b32_e32 v251, 0xffff0000, v180
	v_lshlrev_b32_e32 v192, 16, v172
	v_and_b32_e32 v193, 0xffff0000, v172
	v_max_f32_e32 v250, 0x0da24260, v250
	v_max_f32_e32 v251, 0x0da24260, v251
	v_rcp_f32_e32 v250, v250
	v_rcp_f32_e32 v251, v251
	v_max_f32_e32 v192, 0x0da24260, v192
	v_max_f32_e32 v193, 0x0da24260, v193
	v_mul_f32_e32 v250, v250, v192
	v_mul_f32_e32 v251, v251, v193
	v_mul_f32_e32 v94, v94, v250
	v_mul_f32_e32 v95, v95, v251
	v_lshlrev_b32_e32 v250, 16, v181
	v_and_b32_e32 v251, 0xffff0000, v181
	v_lshlrev_b32_e32 v192, 16, v173
	v_and_b32_e32 v193, 0xffff0000, v173
	v_max_f32_e32 v250, 0x0da24260, v250
	v_max_f32_e32 v251, 0x0da24260, v251
	v_rcp_f32_e32 v250, v250
	v_rcp_f32_e32 v251, v251
	v_max_f32_e32 v192, 0x0da24260, v192
	v_max_f32_e32 v193, 0x0da24260, v193
	v_mul_f32_e32 v250, v250, v192
	v_mul_f32_e32 v251, v251, v193
	v_mul_f32_e32 v96, v96, v250
	v_mul_f32_e32 v97, v97, v251
	v_lshlrev_b32_e32 v250, 16, v182
	v_and_b32_e32 v251, 0xffff0000, v182
	v_lshlrev_b32_e32 v192, 16, v174
	v_and_b32_e32 v193, 0xffff0000, v174
	v_max_f32_e32 v250, 0x0da24260, v250
	v_max_f32_e32 v251, 0x0da24260, v251
	v_rcp_f32_e32 v250, v250
	v_rcp_f32_e32 v251, v251
	v_max_f32_e32 v192, 0x0da24260, v192
	v_max_f32_e32 v193, 0x0da24260, v193
	v_mul_f32_e32 v250, v250, v192
	v_mul_f32_e32 v251, v251, v193
	v_mul_f32_e32 v90, v90, v250
	v_mul_f32_e32 v91, v91, v251
	v_lshlrev_b32_e32 v250, 16, v183
	v_and_b32_e32 v251, 0xffff0000, v183
	v_lshlrev_b32_e32 v192, 16, v175
	v_and_b32_e32 v193, 0xffff0000, v175
	v_max_f32_e32 v250, 0x0da24260, v250
	v_max_f32_e32 v251, 0x0da24260, v251
	v_rcp_f32_e32 v250, v250
	v_rcp_f32_e32 v251, v251
	v_max_f32_e32 v192, 0x0da24260, v192
	v_max_f32_e32 v193, 0x0da24260, v193
	v_mul_f32_e32 v250, v250, v192
	v_mul_f32_e32 v251, v251, v193
	v_mul_f32_e32 v92, v92, v250
	v_mul_f32_e32 v93, v93, v251
	global_load_dwordx4 v[172:175], v248, s[70:71] offset:256
	global_load_dwordx4 v[180:183], v248, s[70:71] offset:2304
	s_waitcnt vmcnt(20)
	v_lshlrev_b32_e32 v250, 16, v188
	v_and_b32_e32 v251, 0xffff0000, v188
	v_lshlrev_b32_e32 v192, 16, v184
	v_and_b32_e32 v193, 0xffff0000, v184
	v_max_f32_e32 v250, 0x0da24260, v250
	v_max_f32_e32 v251, 0x0da24260, v251
	v_rcp_f32_e32 v250, v250
	v_rcp_f32_e32 v251, v251
	v_max_f32_e32 v192, 0x0da24260, v192
	v_max_f32_e32 v193, 0x0da24260, v193
	v_mul_f32_e32 v250, v250, v192
	v_mul_f32_e32 v251, v251, v193
	v_mul_f32_e32 v82, v82, v250
	v_mul_f32_e32 v83, v83, v251
	v_lshlrev_b32_e32 v250, 16, v189
	v_and_b32_e32 v251, 0xffff0000, v189
	v_lshlrev_b32_e32 v192, 16, v185
	v_and_b32_e32 v193, 0xffff0000, v185
	v_max_f32_e32 v250, 0x0da24260, v250
	v_max_f32_e32 v251, 0x0da24260, v251
	v_rcp_f32_e32 v250, v250
	v_rcp_f32_e32 v251, v251
	v_max_f32_e32 v192, 0x0da24260, v192
	v_max_f32_e32 v193, 0x0da24260, v193
	v_mul_f32_e32 v250, v250, v192
	v_mul_f32_e32 v251, v251, v193
	v_mul_f32_e32 v84, v84, v250
	v_mul_f32_e32 v85, v85, v251
	v_lshlrev_b32_e32 v250, 16, v190
	v_and_b32_e32 v251, 0xffff0000, v190
	v_lshlrev_b32_e32 v192, 16, v186
	v_and_b32_e32 v193, 0xffff0000, v186
	v_max_f32_e32 v250, 0x0da24260, v250
	v_max_f32_e32 v251, 0x0da24260, v251
	v_rcp_f32_e32 v250, v250
	v_rcp_f32_e32 v251, v251
	v_max_f32_e32 v192, 0x0da24260, v192
	v_max_f32_e32 v193, 0x0da24260, v193
	v_mul_f32_e32 v250, v250, v192
	v_mul_f32_e32 v251, v251, v193
	v_mul_f32_e32 v74, v74, v250
	v_mul_f32_e32 v75, v75, v251
	v_lshlrev_b32_e32 v250, 16, v191
	v_and_b32_e32 v251, 0xffff0000, v191
	v_lshlrev_b32_e32 v192, 16, v187
	v_and_b32_e32 v193, 0xffff0000, v187
	v_max_f32_e32 v250, 0x0da24260, v250
	v_max_f32_e32 v251, 0x0da24260, v251
	v_rcp_f32_e32 v250, v250
	v_rcp_f32_e32 v251, v251
	v_max_f32_e32 v192, 0x0da24260, v192
	v_max_f32_e32 v193, 0x0da24260, v193
	v_mul_f32_e32 v250, v250, v192
	v_mul_f32_e32 v251, v251, v193
	v_mul_f32_e32 v76, v76, v250
	v_mul_f32_e32 v77, v77, v251
	s_waitcnt vmcnt(18)
	v_lshlrev_b32_e32 v250, 16, v212
	v_and_b32_e32 v251, 0xffff0000, v212
	v_lshlrev_b32_e32 v192, 16, v198
	v_and_b32_e32 v193, 0xffff0000, v198
	v_max_f32_e32 v250, 0x0da24260, v250
	v_max_f32_e32 v251, 0x0da24260, v251
	v_rcp_f32_e32 v250, v250
	v_rcp_f32_e32 v251, v251
	v_max_f32_e32 v192, 0x0da24260, v192
	v_max_f32_e32 v193, 0x0da24260, v193
	v_mul_f32_e32 v250, v250, v192
	v_mul_f32_e32 v251, v251, v193
	v_mul_f32_e32 v86, v86, v250
	v_mul_f32_e32 v87, v87, v251
	v_lshlrev_b32_e32 v250, 16, v213
	v_and_b32_e32 v251, 0xffff0000, v213
	v_lshlrev_b32_e32 v192, 16, v199
	v_and_b32_e32 v193, 0xffff0000, v199
	v_max_f32_e32 v250, 0x0da24260, v250
	v_max_f32_e32 v251, 0x0da24260, v251
	v_rcp_f32_e32 v250, v250
	v_rcp_f32_e32 v251, v251
	v_max_f32_e32 v192, 0x0da24260, v192
	v_max_f32_e32 v193, 0x0da24260, v193
	v_mul_f32_e32 v250, v250, v192
	v_mul_f32_e32 v251, v251, v193
	v_mul_f32_e32 v88, v88, v250
	v_mul_f32_e32 v89, v89, v251
	v_lshlrev_b32_e32 v250, 16, v214
	v_and_b32_e32 v251, 0xffff0000, v214
	v_lshlrev_b32_e32 v192, 16, v200
	v_and_b32_e32 v193, 0xffff0000, v200
	v_max_f32_e32 v250, 0x0da24260, v250
	v_max_f32_e32 v251, 0x0da24260, v251
	v_rcp_f32_e32 v250, v250
	v_rcp_f32_e32 v251, v251
	v_max_f32_e32 v192, 0x0da24260, v192
	v_max_f32_e32 v193, 0x0da24260, v193
	v_mul_f32_e32 v250, v250, v192
	v_mul_f32_e32 v251, v251, v193
	v_mul_f32_e32 v78, v78, v250
	v_mul_f32_e32 v79, v79, v251
	v_lshlrev_b32_e32 v250, 16, v215
	v_and_b32_e32 v251, 0xffff0000, v215
	v_lshlrev_b32_e32 v192, 16, v201
	v_and_b32_e32 v193, 0xffff0000, v201
	v_max_f32_e32 v250, 0x0da24260, v250
	v_max_f32_e32 v251, 0x0da24260, v251
	v_rcp_f32_e32 v250, v250
	v_rcp_f32_e32 v251, v251
	v_max_f32_e32 v192, 0x0da24260, v192
	v_max_f32_e32 v193, 0x0da24260, v193
	v_mul_f32_e32 v250, v250, v192
	v_mul_f32_e32 v251, v251, v193
	v_mul_f32_e32 v80, v80, v250
	v_mul_f32_e32 v81, v81, v251
	s_waitcnt vmcnt(16)
	v_lshlrev_b32_e32 v250, 16, v220
	v_and_b32_e32 v251, 0xffff0000, v220
	v_lshlrev_b32_e32 v192, 16, v216
	v_and_b32_e32 v193, 0xffff0000, v216
	v_max_f32_e32 v250, 0x0da24260, v250
	v_max_f32_e32 v251, 0x0da24260, v251
	v_rcp_f32_e32 v250, v250
	v_rcp_f32_e32 v251, v251
	v_max_f32_e32 v192, 0x0da24260, v192
	v_max_f32_e32 v193, 0x0da24260, v193
	v_mul_f32_e32 v250, v250, v192
	v_mul_f32_e32 v251, v251, v193
	v_mul_f32_e32 v70, v70, v250
	v_mul_f32_e32 v71, v71, v251
	v_lshlrev_b32_e32 v250, 16, v221
	v_and_b32_e32 v251, 0xffff0000, v221
	v_lshlrev_b32_e32 v192, 16, v217
	v_and_b32_e32 v193, 0xffff0000, v217
	v_max_f32_e32 v250, 0x0da24260, v250
	v_max_f32_e32 v251, 0x0da24260, v251
	v_rcp_f32_e32 v250, v250
	v_rcp_f32_e32 v251, v251
	v_max_f32_e32 v192, 0x0da24260, v192
	v_max_f32_e32 v193, 0x0da24260, v193
	v_mul_f32_e32 v250, v250, v192
	v_mul_f32_e32 v251, v251, v193
	v_mul_f32_e32 v72, v72, v250
	v_mul_f32_e32 v73, v73, v251
	v_lshlrev_b32_e32 v250, 16, v222
	v_and_b32_e32 v251, 0xffff0000, v222
	v_lshlrev_b32_e32 v192, 16, v218
	v_and_b32_e32 v193, 0xffff0000, v218
	v_max_f32_e32 v250, 0x0da24260, v250
	v_max_f32_e32 v251, 0x0da24260, v251
	v_rcp_f32_e32 v250, v250
	v_rcp_f32_e32 v251, v251
	v_max_f32_e32 v192, 0x0da24260, v192
	v_max_f32_e32 v193, 0x0da24260, v193
	v_mul_f32_e32 v250, v250, v192
	v_mul_f32_e32 v251, v251, v193
	v_mul_f32_e32 v66, v66, v250
	v_mul_f32_e32 v67, v67, v251
	v_lshlrev_b32_e32 v250, 16, v223
	v_and_b32_e32 v251, 0xffff0000, v223
	v_lshlrev_b32_e32 v192, 16, v219
	v_and_b32_e32 v193, 0xffff0000, v219
	v_max_f32_e32 v250, 0x0da24260, v250
	v_max_f32_e32 v251, 0x0da24260, v251
	v_rcp_f32_e32 v250, v250
	v_rcp_f32_e32 v251, v251
	v_max_f32_e32 v192, 0x0da24260, v192
	v_max_f32_e32 v193, 0x0da24260, v193
	v_mul_f32_e32 v250, v250, v192
	v_mul_f32_e32 v251, v251, v193
	v_mul_f32_e32 v68, v68, v250
	v_mul_f32_e32 v69, v69, v251
	s_waitcnt vmcnt(14)
	v_lshlrev_b32_e32 v250, 16, v228
	v_and_b32_e32 v251, 0xffff0000, v228
	v_lshlrev_b32_e32 v192, 16, v224
	v_and_b32_e32 v193, 0xffff0000, v224
	v_max_f32_e32 v250, 0x0da24260, v250
	v_max_f32_e32 v251, 0x0da24260, v251
	v_rcp_f32_e32 v250, v250
	v_rcp_f32_e32 v251, v251
	v_max_f32_e32 v192, 0x0da24260, v192
	v_max_f32_e32 v193, 0x0da24260, v193
	v_mul_f32_e32 v250, v250, v192
	v_mul_f32_e32 v251, v251, v193
	v_mul_f32_e32 v62, v62, v250
	v_mul_f32_e32 v63, v63, v251
	v_lshlrev_b32_e32 v250, 16, v229
	v_and_b32_e32 v251, 0xffff0000, v229
	v_lshlrev_b32_e32 v192, 16, v225
	v_and_b32_e32 v193, 0xffff0000, v225
	v_max_f32_e32 v250, 0x0da24260, v250
	v_max_f32_e32 v251, 0x0da24260, v251
	v_rcp_f32_e32 v250, v250
	v_rcp_f32_e32 v251, v251
	v_max_f32_e32 v192, 0x0da24260, v192
	v_max_f32_e32 v193, 0x0da24260, v193
	v_mul_f32_e32 v250, v250, v192
	v_mul_f32_e32 v251, v251, v193
	v_mul_f32_e32 v64, v64, v250
	v_mul_f32_e32 v65, v65, v251
	v_lshlrev_b32_e32 v250, 16, v230
	v_and_b32_e32 v251, 0xffff0000, v230
	v_lshlrev_b32_e32 v192, 16, v226
	v_and_b32_e32 v193, 0xffff0000, v226
	v_max_f32_e32 v250, 0x0da24260, v250
	v_max_f32_e32 v251, 0x0da24260, v251
	v_rcp_f32_e32 v250, v250
	v_rcp_f32_e32 v251, v251
	v_max_f32_e32 v192, 0x0da24260, v192
	v_max_f32_e32 v193, 0x0da24260, v193
	v_mul_f32_e32 v250, v250, v192
	v_mul_f32_e32 v251, v251, v193
	v_mul_f32_e32 v58, v58, v250
	v_mul_f32_e32 v59, v59, v251
	v_lshlrev_b32_e32 v250, 16, v231
	v_and_b32_e32 v251, 0xffff0000, v231
	v_lshlrev_b32_e32 v192, 16, v227
	v_and_b32_e32 v193, 0xffff0000, v227
	v_max_f32_e32 v250, 0x0da24260, v250
	v_max_f32_e32 v251, 0x0da24260, v251
	v_rcp_f32_e32 v250, v250
	v_rcp_f32_e32 v251, v251
	v_max_f32_e32 v192, 0x0da24260, v192
	v_max_f32_e32 v193, 0x0da24260, v193
	v_mul_f32_e32 v250, v250, v192
	v_mul_f32_e32 v251, v251, v193
	v_mul_f32_e32 v60, v60, v250
	v_mul_f32_e32 v61, v61, v251
	s_waitcnt vmcnt(12)
	v_lshlrev_b32_e32 v250, 16, v236
	v_and_b32_e32 v251, 0xffff0000, v236
	v_lshlrev_b32_e32 v192, 16, v232
	v_and_b32_e32 v193, 0xffff0000, v232
	v_max_f32_e32 v250, 0x0da24260, v250
	v_max_f32_e32 v251, 0x0da24260, v251
	v_rcp_f32_e32 v250, v250
	v_rcp_f32_e32 v251, v251
	v_max_f32_e32 v192, 0x0da24260, v192
	v_max_f32_e32 v193, 0x0da24260, v193
	v_mul_f32_e32 v250, v250, v192
	v_mul_f32_e32 v251, v251, v193
	v_mul_f32_e32 v50, v50, v250
	v_mul_f32_e32 v51, v51, v251
	v_lshlrev_b32_e32 v250, 16, v237
	v_and_b32_e32 v251, 0xffff0000, v237
	v_lshlrev_b32_e32 v192, 16, v233
	v_and_b32_e32 v193, 0xffff0000, v233
	v_max_f32_e32 v250, 0x0da24260, v250
	v_max_f32_e32 v251, 0x0da24260, v251
	v_rcp_f32_e32 v250, v250
	v_rcp_f32_e32 v251, v251
	v_max_f32_e32 v192, 0x0da24260, v192
	v_max_f32_e32 v193, 0x0da24260, v193
	v_mul_f32_e32 v250, v250, v192
	v_mul_f32_e32 v251, v251, v193
	v_mul_f32_e32 v52, v52, v250
	v_mul_f32_e32 v53, v53, v251
	v_lshlrev_b32_e32 v250, 16, v238
	v_and_b32_e32 v251, 0xffff0000, v238
	v_lshlrev_b32_e32 v192, 16, v234
	v_and_b32_e32 v193, 0xffff0000, v234
	v_max_f32_e32 v250, 0x0da24260, v250
	v_max_f32_e32 v251, 0x0da24260, v251
	v_rcp_f32_e32 v250, v250
	v_rcp_f32_e32 v251, v251
	v_max_f32_e32 v192, 0x0da24260, v192
	v_max_f32_e32 v193, 0x0da24260, v193
	v_mul_f32_e32 v250, v250, v192
	v_mul_f32_e32 v251, v251, v193
	v_mul_f32_e32 v42, v42, v250
	v_mul_f32_e32 v43, v43, v251
	v_lshlrev_b32_e32 v250, 16, v239
	v_and_b32_e32 v251, 0xffff0000, v239
	v_lshlrev_b32_e32 v192, 16, v235
	v_and_b32_e32 v193, 0xffff0000, v235
	v_max_f32_e32 v250, 0x0da24260, v250
	v_max_f32_e32 v251, 0x0da24260, v251
	v_rcp_f32_e32 v250, v250
	v_rcp_f32_e32 v251, v251
	v_max_f32_e32 v192, 0x0da24260, v192
	v_max_f32_e32 v193, 0x0da24260, v193
	v_mul_f32_e32 v250, v250, v192
	v_mul_f32_e32 v251, v251, v193
	v_mul_f32_e32 v44, v44, v250
	v_mul_f32_e32 v45, v45, v251
	s_waitcnt vmcnt(10)
	v_lshlrev_b32_e32 v250, 16, v244
	v_and_b32_e32 v251, 0xffff0000, v244
	v_lshlrev_b32_e32 v192, 16, v240
	v_and_b32_e32 v193, 0xffff0000, v240
	v_max_f32_e32 v250, 0x0da24260, v250
	v_max_f32_e32 v251, 0x0da24260, v251
	v_rcp_f32_e32 v250, v250
	v_rcp_f32_e32 v251, v251
	v_max_f32_e32 v192, 0x0da24260, v192
	v_max_f32_e32 v193, 0x0da24260, v193
	v_mul_f32_e32 v250, v250, v192
	v_mul_f32_e32 v251, v251, v193
	v_mul_f32_e32 v54, v54, v250
	v_mul_f32_e32 v55, v55, v251
	v_lshlrev_b32_e32 v250, 16, v245
	v_and_b32_e32 v251, 0xffff0000, v245
	v_lshlrev_b32_e32 v192, 16, v241
	v_and_b32_e32 v193, 0xffff0000, v241
	v_max_f32_e32 v250, 0x0da24260, v250
	v_max_f32_e32 v251, 0x0da24260, v251
	v_rcp_f32_e32 v250, v250
	v_rcp_f32_e32 v251, v251
	v_max_f32_e32 v192, 0x0da24260, v192
	v_max_f32_e32 v193, 0x0da24260, v193
	v_mul_f32_e32 v250, v250, v192
	v_mul_f32_e32 v251, v251, v193
	v_mul_f32_e32 v56, v56, v250
	v_mul_f32_e32 v57, v57, v251
	v_lshlrev_b32_e32 v250, 16, v246
	v_and_b32_e32 v251, 0xffff0000, v246
	v_lshlrev_b32_e32 v192, 16, v242
	v_and_b32_e32 v193, 0xffff0000, v242
	v_max_f32_e32 v250, 0x0da24260, v250
	v_max_f32_e32 v251, 0x0da24260, v251
	v_rcp_f32_e32 v250, v250
	v_rcp_f32_e32 v251, v251
	v_max_f32_e32 v192, 0x0da24260, v192
	v_max_f32_e32 v193, 0x0da24260, v193
	v_mul_f32_e32 v250, v250, v192
	v_mul_f32_e32 v251, v251, v193
	v_mul_f32_e32 v46, v46, v250
	v_mul_f32_e32 v47, v47, v251
	v_lshlrev_b32_e32 v250, 16, v247
	v_and_b32_e32 v251, 0xffff0000, v247
	v_lshlrev_b32_e32 v192, 16, v243
	v_and_b32_e32 v193, 0xffff0000, v243
	v_max_f32_e32 v250, 0x0da24260, v250
	v_max_f32_e32 v251, 0x0da24260, v251
	v_rcp_f32_e32 v250, v250
	v_rcp_f32_e32 v251, v251
	v_max_f32_e32 v192, 0x0da24260, v192
	v_max_f32_e32 v193, 0x0da24260, v193
	v_mul_f32_e32 v250, v250, v192
	v_mul_f32_e32 v251, v251, v193
	v_mul_f32_e32 v48, v48, v250
	v_mul_f32_e32 v49, v49, v251
	s_waitcnt vmcnt(8)
	v_lshlrev_b32_e32 v250, 16, v134
	v_and_b32_e32 v251, 0xffff0000, v134
	v_lshlrev_b32_e32 v192, 16, v130
	v_and_b32_e32 v193, 0xffff0000, v130
	v_max_f32_e32 v250, 0x0da24260, v250
	v_max_f32_e32 v251, 0x0da24260, v251
	v_rcp_f32_e32 v250, v250
	v_rcp_f32_e32 v251, v251
	v_max_f32_e32 v192, 0x0da24260, v192
	v_max_f32_e32 v193, 0x0da24260, v193
	v_mul_f32_e32 v250, v250, v192
	v_mul_f32_e32 v251, v251, v193
	v_mul_f32_e32 v38, v38, v250
	v_mul_f32_e32 v39, v39, v251
	v_lshlrev_b32_e32 v250, 16, v135
	v_and_b32_e32 v251, 0xffff0000, v135
	v_lshlrev_b32_e32 v192, 16, v131
	v_and_b32_e32 v193, 0xffff0000, v131
	v_max_f32_e32 v250, 0x0da24260, v250
	v_max_f32_e32 v251, 0x0da24260, v251
	v_rcp_f32_e32 v250, v250
	v_rcp_f32_e32 v251, v251
	v_max_f32_e32 v192, 0x0da24260, v192
	v_max_f32_e32 v193, 0x0da24260, v193
	v_mul_f32_e32 v250, v250, v192
	v_mul_f32_e32 v251, v251, v193
	v_mul_f32_e32 v40, v40, v250
	v_mul_f32_e32 v41, v41, v251
	v_lshlrev_b32_e32 v250, 16, v136
	v_and_b32_e32 v251, 0xffff0000, v136
	v_lshlrev_b32_e32 v192, 16, v132
	v_and_b32_e32 v193, 0xffff0000, v132
	v_max_f32_e32 v250, 0x0da24260, v250
	v_max_f32_e32 v251, 0x0da24260, v251
	v_rcp_f32_e32 v250, v250
	v_rcp_f32_e32 v251, v251
	v_max_f32_e32 v192, 0x0da24260, v192
	v_max_f32_e32 v193, 0x0da24260, v193
	v_mul_f32_e32 v250, v250, v192
	v_mul_f32_e32 v251, v251, v193
	v_mul_f32_e32 v34, v34, v250
	v_mul_f32_e32 v35, v35, v251
	v_lshlrev_b32_e32 v250, 16, v137
	v_and_b32_e32 v251, 0xffff0000, v137
	v_lshlrev_b32_e32 v192, 16, v133
	v_and_b32_e32 v193, 0xffff0000, v133
	v_max_f32_e32 v250, 0x0da24260, v250
	v_max_f32_e32 v251, 0x0da24260, v251
	v_rcp_f32_e32 v250, v250
	v_rcp_f32_e32 v251, v251
	v_max_f32_e32 v192, 0x0da24260, v192
	v_max_f32_e32 v193, 0x0da24260, v193
	v_mul_f32_e32 v250, v250, v192
	v_mul_f32_e32 v251, v251, v193
	v_mul_f32_e32 v36, v36, v250
	v_mul_f32_e32 v37, v37, v251
	s_waitcnt vmcnt(6)
	v_lshlrev_b32_e32 v250, 16, v142
	v_and_b32_e32 v251, 0xffff0000, v142
	v_lshlrev_b32_e32 v192, 16, v138
	v_and_b32_e32 v193, 0xffff0000, v138
	v_max_f32_e32 v250, 0x0da24260, v250
	v_max_f32_e32 v251, 0x0da24260, v251
	v_rcp_f32_e32 v250, v250
	v_rcp_f32_e32 v251, v251
	v_max_f32_e32 v192, 0x0da24260, v192
	v_max_f32_e32 v193, 0x0da24260, v193
	v_mul_f32_e32 v250, v250, v192
	v_mul_f32_e32 v251, v251, v193
	v_mul_f32_e32 v30, v30, v250
	v_mul_f32_e32 v31, v31, v251
	v_lshlrev_b32_e32 v250, 16, v143
	v_and_b32_e32 v251, 0xffff0000, v143
	v_lshlrev_b32_e32 v192, 16, v139
	v_and_b32_e32 v193, 0xffff0000, v139
	v_max_f32_e32 v250, 0x0da24260, v250
	v_max_f32_e32 v251, 0x0da24260, v251
	v_rcp_f32_e32 v250, v250
	v_rcp_f32_e32 v251, v251
	v_max_f32_e32 v192, 0x0da24260, v192
	v_max_f32_e32 v193, 0x0da24260, v193
	v_mul_f32_e32 v250, v250, v192
	v_mul_f32_e32 v251, v251, v193
	v_mul_f32_e32 v32, v32, v250
	v_mul_f32_e32 v33, v33, v251
	v_lshlrev_b32_e32 v250, 16, v144
	v_and_b32_e32 v251, 0xffff0000, v144
	v_lshlrev_b32_e32 v192, 16, v140
	v_and_b32_e32 v193, 0xffff0000, v140
	v_max_f32_e32 v250, 0x0da24260, v250
	v_max_f32_e32 v251, 0x0da24260, v251
	v_rcp_f32_e32 v250, v250
	v_rcp_f32_e32 v251, v251
	v_max_f32_e32 v192, 0x0da24260, v192
	v_max_f32_e32 v193, 0x0da24260, v193
	v_mul_f32_e32 v250, v250, v192
	v_mul_f32_e32 v251, v251, v193
	v_mul_f32_e32 v26, v26, v250
	v_mul_f32_e32 v27, v27, v251
	v_lshlrev_b32_e32 v250, 16, v145
	v_and_b32_e32 v251, 0xffff0000, v145
	v_lshlrev_b32_e32 v192, 16, v141
	v_and_b32_e32 v193, 0xffff0000, v141
	v_max_f32_e32 v250, 0x0da24260, v250
	v_max_f32_e32 v251, 0x0da24260, v251
	v_rcp_f32_e32 v250, v250
	v_rcp_f32_e32 v251, v251
	v_max_f32_e32 v192, 0x0da24260, v192
	v_max_f32_e32 v193, 0x0da24260, v193
	v_mul_f32_e32 v250, v250, v192
	v_mul_f32_e32 v251, v251, v193
	v_mul_f32_e32 v28, v28, v250
	v_mul_f32_e32 v29, v29, v251
	s_waitcnt vmcnt(4)
	v_lshlrev_b32_e32 v250, 16, v150
	v_and_b32_e32 v251, 0xffff0000, v150
	v_lshlrev_b32_e32 v192, 16, v146
	v_and_b32_e32 v193, 0xffff0000, v146
	v_max_f32_e32 v250, 0x0da24260, v250
	v_max_f32_e32 v251, 0x0da24260, v251
	v_rcp_f32_e32 v250, v250
	v_rcp_f32_e32 v251, v251
	v_max_f32_e32 v192, 0x0da24260, v192
	v_max_f32_e32 v193, 0x0da24260, v193
	v_mul_f32_e32 v250, v250, v192
	v_mul_f32_e32 v251, v251, v193
	v_mul_f32_e32 v18, v18, v250
	v_mul_f32_e32 v19, v19, v251
	v_lshlrev_b32_e32 v250, 16, v151
	v_and_b32_e32 v251, 0xffff0000, v151
	v_lshlrev_b32_e32 v192, 16, v147
	v_and_b32_e32 v193, 0xffff0000, v147
	v_max_f32_e32 v250, 0x0da24260, v250
	v_max_f32_e32 v251, 0x0da24260, v251
	v_rcp_f32_e32 v250, v250
	v_rcp_f32_e32 v251, v251
	v_max_f32_e32 v192, 0x0da24260, v192
	v_max_f32_e32 v193, 0x0da24260, v193
	v_mul_f32_e32 v250, v250, v192
	v_mul_f32_e32 v251, v251, v193
	v_mul_f32_e32 v20, v20, v250
	v_mul_f32_e32 v21, v21, v251
	v_lshlrev_b32_e32 v250, 16, v152
	v_and_b32_e32 v251, 0xffff0000, v152
	v_lshlrev_b32_e32 v192, 16, v148
	v_and_b32_e32 v193, 0xffff0000, v148
	v_max_f32_e32 v250, 0x0da24260, v250
	v_max_f32_e32 v251, 0x0da24260, v251
	v_rcp_f32_e32 v250, v250
	v_rcp_f32_e32 v251, v251
	v_max_f32_e32 v192, 0x0da24260, v192
	v_max_f32_e32 v193, 0x0da24260, v193
	v_mul_f32_e32 v250, v250, v192
	v_mul_f32_e32 v251, v251, v193
	v_mul_f32_e32 v10, v10, v250
	v_mul_f32_e32 v11, v11, v251
	v_lshlrev_b32_e32 v250, 16, v153
	v_and_b32_e32 v251, 0xffff0000, v153
	v_lshlrev_b32_e32 v192, 16, v149
	v_and_b32_e32 v193, 0xffff0000, v149
	v_max_f32_e32 v250, 0x0da24260, v250
	v_max_f32_e32 v251, 0x0da24260, v251
	v_rcp_f32_e32 v250, v250
	v_rcp_f32_e32 v251, v251
	v_max_f32_e32 v192, 0x0da24260, v192
	v_max_f32_e32 v193, 0x0da24260, v193
	v_mul_f32_e32 v250, v250, v192
	v_mul_f32_e32 v251, v251, v193
	v_mul_f32_e32 v12, v12, v250
	v_mul_f32_e32 v13, v13, v251
	s_waitcnt vmcnt(2)
	v_lshlrev_b32_e32 v250, 16, v168
	v_and_b32_e32 v251, 0xffff0000, v168
	v_lshlrev_b32_e32 v192, 16, v164
	v_and_b32_e32 v193, 0xffff0000, v164
	v_max_f32_e32 v250, 0x0da24260, v250
	v_max_f32_e32 v251, 0x0da24260, v251
	v_rcp_f32_e32 v250, v250
	v_rcp_f32_e32 v251, v251
	v_max_f32_e32 v192, 0x0da24260, v192
	v_max_f32_e32 v193, 0x0da24260, v193
	v_mul_f32_e32 v250, v250, v192
	v_mul_f32_e32 v251, v251, v193
	v_mul_f32_e32 v22, v22, v250
	v_mul_f32_e32 v23, v23, v251
	v_lshlrev_b32_e32 v250, 16, v169
	v_and_b32_e32 v251, 0xffff0000, v169
	v_lshlrev_b32_e32 v192, 16, v165
	v_and_b32_e32 v193, 0xffff0000, v165
	v_max_f32_e32 v250, 0x0da24260, v250
	v_max_f32_e32 v251, 0x0da24260, v251
	v_rcp_f32_e32 v250, v250
	v_rcp_f32_e32 v251, v251
	v_max_f32_e32 v192, 0x0da24260, v192
	v_max_f32_e32 v193, 0x0da24260, v193
	v_mul_f32_e32 v250, v250, v192
	v_mul_f32_e32 v251, v251, v193
	v_mul_f32_e32 v24, v24, v250
	v_mul_f32_e32 v25, v25, v251
	v_lshlrev_b32_e32 v250, 16, v170
	v_and_b32_e32 v251, 0xffff0000, v170
	v_lshlrev_b32_e32 v192, 16, v166
	v_and_b32_e32 v193, 0xffff0000, v166
	v_max_f32_e32 v250, 0x0da24260, v250
	v_max_f32_e32 v251, 0x0da24260, v251
	v_rcp_f32_e32 v250, v250
	v_rcp_f32_e32 v251, v251
	v_max_f32_e32 v192, 0x0da24260, v192
	v_max_f32_e32 v193, 0x0da24260, v193
	v_mul_f32_e32 v250, v250, v192
	v_mul_f32_e32 v251, v251, v193
	v_mul_f32_e32 v14, v14, v250
	v_mul_f32_e32 v15, v15, v251
	v_lshlrev_b32_e32 v250, 16, v171
	v_and_b32_e32 v251, 0xffff0000, v171
	v_lshlrev_b32_e32 v192, 16, v167
	v_and_b32_e32 v193, 0xffff0000, v167
	v_max_f32_e32 v250, 0x0da24260, v250
	v_max_f32_e32 v251, 0x0da24260, v251
	v_rcp_f32_e32 v250, v250
	v_rcp_f32_e32 v251, v251
	v_max_f32_e32 v192, 0x0da24260, v192
	v_max_f32_e32 v193, 0x0da24260, v193
	v_mul_f32_e32 v250, v250, v192
	v_mul_f32_e32 v251, v251, v193
	v_mul_f32_e32 v16, v16, v250
	v_mul_f32_e32 v17, v17, v251
	s_waitcnt vmcnt(0)
	v_lshlrev_b32_e32 v250, 16, v180
	v_and_b32_e32 v251, 0xffff0000, v180
	v_lshlrev_b32_e32 v192, 16, v172
	v_and_b32_e32 v193, 0xffff0000, v172
	v_max_f32_e32 v250, 0x0da24260, v250
	v_max_f32_e32 v251, 0x0da24260, v251
	v_rcp_f32_e32 v250, v250
	v_rcp_f32_e32 v251, v251
	v_max_f32_e32 v192, 0x0da24260, v192
	v_max_f32_e32 v193, 0x0da24260, v193
	v_mul_f32_e32 v250, v250, v192
	v_mul_f32_e32 v251, v251, v193
	v_mul_f32_e32 v6, v6, v250
	v_mul_f32_e32 v7, v7, v251
	v_lshlrev_b32_e32 v250, 16, v181
	v_and_b32_e32 v251, 0xffff0000, v181
	v_lshlrev_b32_e32 v192, 16, v173
	v_and_b32_e32 v193, 0xffff0000, v173
	v_max_f32_e32 v250, 0x0da24260, v250
	v_max_f32_e32 v251, 0x0da24260, v251
	v_rcp_f32_e32 v250, v250
	v_rcp_f32_e32 v251, v251
	v_max_f32_e32 v192, 0x0da24260, v192
	v_max_f32_e32 v193, 0x0da24260, v193
	v_mul_f32_e32 v250, v250, v192
	v_mul_f32_e32 v251, v251, v193
	v_mul_f32_e32 v8, v8, v250
	v_mul_f32_e32 v9, v9, v251
	v_lshlrev_b32_e32 v250, 16, v182
	v_and_b32_e32 v251, 0xffff0000, v182
	v_lshlrev_b32_e32 v192, 16, v174
	v_and_b32_e32 v193, 0xffff0000, v174
	v_max_f32_e32 v250, 0x0da24260, v250
	v_max_f32_e32 v251, 0x0da24260, v251
	v_rcp_f32_e32 v250, v250
	v_rcp_f32_e32 v251, v251
	v_max_f32_e32 v192, 0x0da24260, v192
	v_max_f32_e32 v193, 0x0da24260, v193
	v_mul_f32_e32 v250, v250, v192
	v_mul_f32_e32 v251, v251, v193
	v_mul_f32_e32 v2, v2, v250
	v_mul_f32_e32 v3, v3, v251
	v_lshlrev_b32_e32 v250, 16, v183
	v_and_b32_e32 v251, 0xffff0000, v183
	v_lshlrev_b32_e32 v192, 16, v175
	v_and_b32_e32 v193, 0xffff0000, v175
	v_max_f32_e32 v250, 0x0da24260, v250
	v_max_f32_e32 v251, 0x0da24260, v251
	v_rcp_f32_e32 v250, v250
	v_rcp_f32_e32 v251, v251
	v_max_f32_e32 v192, 0x0da24260, v192
	v_max_f32_e32 v193, 0x0da24260, v193
	v_mul_f32_e32 v250, v250, v192
	v_mul_f32_e32 v251, v251, v193
	v_mul_f32_e32 v4, v4, v250
	v_mul_f32_e32 v5, v5, v251
	s_branch .Lm_done
.Lm_final:
	global_load_dwordx4 v[130:133], v248, s[56:57]
	global_load_dwordx4 v[134:137], v248, s[56:57] offset:256
	global_load_dwordx4 v[138:141], v248, s[58:59]
	global_load_dwordx4 v[142:145], v248, s[58:59] offset:256
	global_load_dwordx4 v[146:149], v248, s[60:61]
	global_load_dwordx4 v[150:153], v248, s[60:61] offset:256
	global_load_dwordx4 v[164:167], v248, s[62:63]
	global_load_dwordx4 v[168:171], v248, s[62:63] offset:256
	global_load_dwordx4 v[172:175], v248, s[64:65]
	global_load_dwordx4 v[180:183], v248, s[64:65] offset:256
	global_load_dwordx4 v[184:187], v248, s[66:67]
	global_load_dwordx4 v[188:191], v248, s[66:67] offset:256
	global_load_dwordx4 v[198:201], v248, s[68:69]
	global_load_dwordx4 v[212:215], v248, s[68:69] offset:256
	global_load_dwordx4 v[216:219], v248, s[70:71]
	global_load_dwordx4 v[220:223], v248, s[70:71] offset:256
	s_waitcnt vmcnt(15)
	v_lshlrev_b32_e32 v250, 16, v130
	v_and_b32_e32 v130, 0xffff0000, v130
	v_lshlrev_b32_e32 v192, 16, v131
	v_and_b32_e32 v131, 0xffff0000, v131
	v_max_f32_e32 v250, 0x0da24260, v250
	v_max_f32_e32 v130, 0x0da24260, v130
	v_max_f32_e32 v192, 0x0da24260, v192
	v_max_f32_e32 v131, 0x0da24260, v131
	v_mul_f32_e32 v250, v126, v250
	v_mul_f32_e32 v130, v127, v130
	v_mul_f32_e32 v192, v128, v192
	v_mul_f32_e32 v131, v129, v131
	v_cvt_pk_bf16_f32 v130, v250, v130
	v_cvt_pk_bf16_f32 v131, v192, v131
	v_lshlrev_b32_e32 v250, 16, v132
	v_and_b32_e32 v132, 0xffff0000, v132
	v_lshlrev_b32_e32 v192, 16, v133
	v_and_b32_e32 v133, 0xffff0000, v133
	v_max_f32_e32 v250, 0x0da24260, v250
	v_max_f32_e32 v132, 0x0da24260, v132
	v_max_f32_e32 v192, 0x0da24260, v192
	v_max_f32_e32 v133, 0x0da24260, v133
	v_mul_f32_e32 v250, v122, v250
	v_mul_f32_e32 v132, v123, v132
	v_mul_f32_e32 v192, v124, v192
	v_mul_f32_e32 v133, v125, v133
	v_cvt_pk_bf16_f32 v132, v250, v132
	v_cvt_pk_bf16_f32 v133, v192, v133
	global_store_dwordx4 v249, v[130:133], s[82:83]
	s_waitcnt vmcnt(15)
	v_lshlrev_b32_e32 v250, 16, v134
	v_and_b32_e32 v134, 0xffff0000, v134
	v_lshlrev_b32_e32 v192, 16, v135
	v_and_b32_e32 v135, 0xffff0000, v135
	v_max_f32_e32 v250, 0x0da24260, v250
	v_max_f32_e32 v134, 0x0da24260, v134
	v_max_f32_e32 v192, 0x0da24260, v192
	v_max_f32_e32 v135, 0x0da24260, v135
	v_mul_f32_e32 v250, v114, v250
	v_mul_f32_e32 v134, v115, v134
	v_mul_f32_e32 v192, v116, v192
	v_mul_f32_e32 v135, v117, v135
	v_cvt_pk_bf16_f32 v134, v250, v134
	v_cvt_pk_bf16_f32 v135, v192, v135
	v_lshlrev_b32_e32 v250, 16, v136
	v_and_b32_e32 v136, 0xffff0000, v136
	v_lshlrev_b32_e32 v192, 16, v137
	v_and_b32_e32 v137, 0xffff0000, v137
	v_max_f32_e32 v250, 0x0da24260, v250
	v_max_f32_e32 v136, 0x0da24260, v136
	v_max_f32_e32 v192, 0x0da24260, v192
	v_max_f32_e32 v137, 0x0da24260, v137
	v_mul_f32_e32 v250, v106, v250
	v_mul_f32_e32 v136, v107, v136
	v_mul_f32_e32 v192, v108, v192
	v_mul_f32_e32 v137, v109, v137
	v_cvt_pk_bf16_f32 v136, v250, v136
	v_cvt_pk_bf16_f32 v137, v192, v137
	global_store_dwordx4 v249, v[134:137], s[82:83] offset:256
	s_waitcnt vmcnt(15)
	v_lshlrev_b32_e32 v250, 16, v138
	v_and_b32_e32 v138, 0xffff0000, v138
	v_lshlrev_b32_e32 v192, 16, v139
	v_and_b32_e32 v139, 0xffff0000, v139
	v_max_f32_e32 v250, 0x0da24260, v250
	v_max_f32_e32 v138, 0x0da24260, v138
	v_max_f32_e32 v192, 0x0da24260, v192
	v_max_f32_e32 v139, 0x0da24260, v139
	v_mul_f32_e32 v250, v118, v250
	v_mul_f32_e32 v138, v119, v138
	v_mul_f32_e32 v192, v120, v192
	v_mul_f32_e32 v139, v121, v139
	v_cvt_pk_bf16_f32 v138, v250, v138
	v_cvt_pk_bf16_f32 v139, v192, v139
	v_lshlrev_b32_e32 v250, 16, v140
	v_and_b32_e32 v140, 0xffff0000, v140
	v_lshlrev_b32_e32 v192, 16, v141
	v_and_b32_e32 v141, 0xffff0000, v141
	v_max_f32_e32 v250, 0x0da24260, v250
	v_max_f32_e32 v140, 0x0da24260, v140
	v_max_f32_e32 v192, 0x0da24260, v192
	v_max_f32_e32 v141, 0x0da24260, v141
	v_mul_f32_e32 v250, v110, v250
	v_mul_f32_e32 v140, v111, v140
	v_mul_f32_e32 v192, v112, v192
	v_mul_f32_e32 v141, v113, v141
	v_cvt_pk_bf16_f32 v140, v250, v140
	v_cvt_pk_bf16_f32 v141, v192, v141
	global_store_dwordx4 v249, v[138:141], s[84:85]
	s_waitcnt vmcnt(15)
	v_lshlrev_b32_e32 v250, 16, v142
	v_and_b32_e32 v142, 0xffff0000, v142
	v_lshlrev_b32_e32 v192, 16, v143
	v_and_b32_e32 v143, 0xffff0000, v143
	v_max_f32_e32 v250, 0x0da24260, v250
	v_max_f32_e32 v142, 0x0da24260, v142
	v_max_f32_e32 v192, 0x0da24260, v192
	v_max_f32_e32 v143, 0x0da24260, v143
	v_mul_f32_e32 v250, v102, v250
	v_mul_f32_e32 v142, v103, v142
	v_mul_f32_e32 v192, v104, v192
	v_mul_f32_e32 v143, v105, v143
	v_cvt_pk_bf16_f32 v142, v250, v142
	v_cvt_pk_bf16_f32 v143, v192, v143
	v_lshlrev_b32_e32 v250, 16, v144
	v_and_b32_e32 v144, 0xffff0000, v144
	v_lshlrev_b32_e32 v192, 16, v145
	v_and_b32_e32 v145, 0xffff0000, v145
	v_max_f32_e32 v250, 0x0da24260, v250
	v_max_f32_e32 v144, 0x0da24260, v144
	v_max_f32_e32 v192, 0x0da24260, v192
	v_max_f32_e32 v145, 0x0da24260, v145
	v_mul_f32_e32 v250, v98, v250
	v_mul_f32_e32 v144, v99, v144
	v_mul_f32_e32 v192, v100, v192
	v_mul_f32_e32 v145, v101, v145
	v_cvt_pk_bf16_f32 v144, v250, v144
	v_cvt_pk_bf16_f32 v145, v192, v145
	global_store_dwordx4 v249, v[142:145], s[84:85] offset:256
	s_waitcnt vmcnt(15)
	v_lshlrev_b32_e32 v250, 16, v146
	v_and_b32_e32 v146, 0xffff0000, v146
	v_lshlrev_b32_e32 v192, 16, v147
	v_and_b32_e32 v147, 0xffff0000, v147
	v_max_f32_e32 v250, 0x0da24260, v250
	v_max_f32_e32 v146, 0x0da24260, v146
	v_max_f32_e32 v192, 0x0da24260, v192
	v_max_f32_e32 v147, 0x0da24260, v147
	v_mul_f32_e32 v250, v94, v250
	v_mul_f32_e32 v146, v95, v146
	v_mul_f32_e32 v192, v96, v192
	v_mul_f32_e32 v147, v97, v147
	v_cvt_pk_bf16_f32 v146, v250, v146
	v_cvt_pk_bf16_f32 v147, v192, v147
	v_lshlrev_b32_e32 v250, 16, v148
	v_and_b32_e32 v148, 0xffff0000, v148
	v_lshlrev_b32_e32 v192, 16, v149
	v_and_b32_e32 v149, 0xffff0000, v149
	v_max_f32_e32 v250, 0x0da24260, v250
	v_max_f32_e32 v148, 0x0da24260, v148
	v_max_f32_e32 v192, 0x0da24260, v192
	v_max_f32_e32 v149, 0x0da24260, v149
	v_mul_f32_e32 v250, v90, v250
	v_mul_f32_e32 v148, v91, v148
	v_mul_f32_e32 v192, v92, v192
	v_mul_f32_e32 v149, v93, v149
	v_cvt_pk_bf16_f32 v148, v250, v148
	v_cvt_pk_bf16_f32 v149, v192, v149
	global_store_dwordx4 v249, v[146:149], s[86:87]
	s_waitcnt vmcnt(15)
	v_lshlrev_b32_e32 v250, 16, v150
	v_and_b32_e32 v150, 0xffff0000, v150
	v_lshlrev_b32_e32 v192, 16, v151
	v_and_b32_e32 v151, 0xffff0000, v151
	v_max_f32_e32 v250, 0x0da24260, v250
	v_max_f32_e32 v150, 0x0da24260, v150
	v_max_f32_e32 v192, 0x0da24260, v192
	v_max_f32_e32 v151, 0x0da24260, v151
	v_mul_f32_e32 v250, v82, v250
	v_mul_f32_e32 v150, v83, v150
	v_mul_f32_e32 v192, v84, v192
	v_mul_f32_e32 v151, v85, v151
	v_cvt_pk_bf16_f32 v150, v250, v150
	v_cvt_pk_bf16_f32 v151, v192, v151
	v_lshlrev_b32_e32 v250, 16, v152
	v_and_b32_e32 v152, 0xffff0000, v152
	v_lshlrev_b32_e32 v192, 16, v153
	v_and_b32_e32 v153, 0xffff0000, v153
	v_max_f32_e32 v250, 0x0da24260, v250
	v_max_f32_e32 v152, 0x0da24260, v152
	v_max_f32_e32 v192, 0x0da24260, v192
	v_max_f32_e32 v153, 0x0da24260, v153
	v_mul_f32_e32 v250, v74, v250
	v_mul_f32_e32 v152, v75, v152
	v_mul_f32_e32 v192, v76, v192
	v_mul_f32_e32 v153, v77, v153
	v_cvt_pk_bf16_f32 v152, v250, v152
	v_cvt_pk_bf16_f32 v153, v192, v153
	global_store_dwordx4 v249, v[150:153], s[86:87] offset:256
	s_waitcnt vmcnt(15)
	v_lshlrev_b32_e32 v250, 16, v164
	v_and_b32_e32 v164, 0xffff0000, v164
	v_lshlrev_b32_e32 v192, 16, v165
	v_and_b32_e32 v165, 0xffff0000, v165
	v_max_f32_e32 v250, 0x0da24260, v250
	v_max_f32_e32 v164, 0x0da24260, v164
	v_max_f32_e32 v192, 0x0da24260, v192
	v_max_f32_e32 v165, 0x0da24260, v165
	v_mul_f32_e32 v250, v86, v250
	v_mul_f32_e32 v164, v87, v164
	v_mul_f32_e32 v192, v88, v192
	v_mul_f32_e32 v165, v89, v165
	v_cvt_pk_bf16_f32 v164, v250, v164
	v_cvt_pk_bf16_f32 v165, v192, v165
	v_lshlrev_b32_e32 v250, 16, v166
	v_and_b32_e32 v166, 0xffff0000, v166
	v_lshlrev_b32_e32 v192, 16, v167
	v_and_b32_e32 v167, 0xffff0000, v167
	v_max_f32_e32 v250, 0x0da24260, v250
	v_max_f32_e32 v166, 0x0da24260, v166
	v_max_f32_e32 v192, 0x0da24260, v192
	v_max_f32_e32 v167, 0x0da24260, v167
	v_mul_f32_e32 v250, v78, v250
	v_mul_f32_e32 v166, v79, v166
	v_mul_f32_e32 v192, v80, v192
	v_mul_f32_e32 v167, v81, v167
	v_cvt_pk_bf16_f32 v166, v250, v166
	v_cvt_pk_bf16_f32 v167, v192, v167
	global_store_dwordx4 v249, v[164:167], s[88:89]
	s_waitcnt vmcnt(15)
	v_lshlrev_b32_e32 v250, 16, v168
	v_and_b32_e32 v168, 0xffff0000, v168
	v_lshlrev_b32_e32 v192, 16, v169
	v_and_b32_e32 v169, 0xffff0000, v169
	v_max_f32_e32 v250, 0x0da24260, v250
	v_max_f32_e32 v168, 0x0da24260, v168
	v_max_f32_e32 v192, 0x0da24260, v192
	v_max_f32_e32 v169, 0x0da24260, v169
	v_mul_f32_e32 v250, v70, v250
	v_mul_f32_e32 v168, v71, v168
	v_mul_f32_e32 v192, v72, v192
	v_mul_f32_e32 v169, v73, v169
	v_cvt_pk_bf16_f32 v168, v250, v168
	v_cvt_pk_bf16_f32 v169, v192, v169
	v_lshlrev_b32_e32 v250, 16, v170
	v_and_b32_e32 v170, 0xffff0000, v170
	v_lshlrev_b32_e32 v192, 16, v171
	v_and_b32_e32 v171, 0xffff0000, v171
	v_max_f32_e32 v250, 0x0da24260, v250
	v_max_f32_e32 v170, 0x0da24260, v170
	v_max_f32_e32 v192, 0x0da24260, v192
	v_max_f32_e32 v171, 0x0da24260, v171
	v_mul_f32_e32 v250, v66, v250
	v_mul_f32_e32 v170, v67, v170
	v_mul_f32_e32 v192, v68, v192
	v_mul_f32_e32 v171, v69, v171
	v_cvt_pk_bf16_f32 v170, v250, v170
	v_cvt_pk_bf16_f32 v171, v192, v171
	global_store_dwordx4 v249, v[168:171], s[88:89] offset:256
	s_waitcnt vmcnt(15)
	v_lshlrev_b32_e32 v250, 16, v172
	v_and_b32_e32 v172, 0xffff0000, v172
	v_lshlrev_b32_e32 v192, 16, v173
	v_and_b32_e32 v173, 0xffff0000, v173
	v_max_f32_e32 v250, 0x0da24260, v250
	v_max_f32_e32 v172, 0x0da24260, v172
	v_max_f32_e32 v192, 0x0da24260, v192
	v_max_f32_e32 v173, 0x0da24260, v173
	v_mul_f32_e32 v250, v62, v250
	v_mul_f32_e32 v172, v63, v172
	v_mul_f32_e32 v192, v64, v192
	v_mul_f32_e32 v173, v65, v173
	v_cvt_pk_bf16_f32 v172, v250, v172
	v_cvt_pk_bf16_f32 v173, v192, v173
	v_lshlrev_b32_e32 v250, 16, v174
	v_and_b32_e32 v174, 0xffff0000, v174
	v_lshlrev_b32_e32 v192, 16, v175
	v_and_b32_e32 v175, 0xffff0000, v175
	v_max_f32_e32 v250, 0x0da24260, v250
	v_max_f32_e32 v174, 0x0da24260, v174
	v_max_f32_e32 v192, 0x0da24260, v192
	v_max_f32_e32 v175, 0x0da24260, v175
	v_mul_f32_e32 v250, v58, v250
	v_mul_f32_e32 v174, v59, v174
	v_mul_f32_e32 v192, v60, v192
	v_mul_f32_e32 v175, v61, v175
	v_cvt_pk_bf16_f32 v174, v250, v174
	v_cvt_pk_bf16_f32 v175, v192, v175
	global_store_dwordx4 v249, v[172:175], s[90:91]
	s_waitcnt vmcnt(15)
	v_lshlrev_b32_e32 v250, 16, v180
	v_and_b32_e32 v180, 0xffff0000, v180
	v_lshlrev_b32_e32 v192, 16, v181
	v_and_b32_e32 v181, 0xffff0000, v181
	v_max_f32_e32 v250, 0x0da24260, v250
	v_max_f32_e32 v180, 0x0da24260, v180
	v_max_f32_e32 v192, 0x0da24260, v192
	v_max_f32_e32 v181, 0x0da24260, v181
	v_mul_f32_e32 v250, v50, v250
	v_mul_f32_e32 v180, v51, v180
	v_mul_f32_e32 v192, v52, v192
	v_mul_f32_e32 v181, v53, v181
	v_cvt_pk_bf16_f32 v180, v250, v180
	v_cvt_pk_bf16_f32 v181, v192, v181
	v_lshlrev_b32_e32 v250, 16, v182
	v_and_b32_e32 v182, 0xffff0000, v182
	v_lshlrev_b32_e32 v192, 16, v183
	v_and_b32_e32 v183, 0xffff0000, v183
	v_max_f32_e32 v250, 0x0da24260, v250
	v_max_f32_e32 v182, 0x0da24260, v182
	v_max_f32_e32 v192, 0x0da24260, v192
	v_max_f32_e32 v183, 0x0da24260, v183
	v_mul_f32_e32 v250, v42, v250
	v_mul_f32_e32 v182, v43, v182
	v_mul_f32_e32 v192, v44, v192
	v_mul_f32_e32 v183, v45, v183
	v_cvt_pk_bf16_f32 v182, v250, v182
	v_cvt_pk_bf16_f32 v183, v192, v183
	global_store_dwordx4 v249, v[180:183], s[90:91] offset:256
	s_waitcnt vmcnt(15)
	v_lshlrev_b32_e32 v250, 16, v184
	v_and_b32_e32 v184, 0xffff0000, v184
	v_lshlrev_b32_e32 v192, 16, v185
	v_and_b32_e32 v185, 0xffff0000, v185
	v_max_f32_e32 v250, 0x0da24260, v250
	v_max_f32_e32 v184, 0x0da24260, v184
	v_max_f32_e32 v192, 0x0da24260, v192
	v_max_f32_e32 v185, 0x0da24260, v185
	v_mul_f32_e32 v250, v54, v250
	v_mul_f32_e32 v184, v55, v184
	v_mul_f32_e32 v192, v56, v192
	v_mul_f32_e32 v185, v57, v185
	v_cvt_pk_bf16_f32 v184, v250, v184
	v_cvt_pk_bf16_f32 v185, v192, v185
	v_lshlrev_b32_e32 v250, 16, v186
	v_and_b32_e32 v186, 0xffff0000, v186
	v_lshlrev_b32_e32 v192, 16, v187
	v_and_b32_e32 v187, 0xffff0000, v187
	v_max_f32_e32 v250, 0x0da24260, v250
	v_max_f32_e32 v186, 0x0da24260, v186
	v_max_f32_e32 v192, 0x0da24260, v192
	v_max_f32_e32 v187, 0x0da24260, v187
	v_mul_f32_e32 v250, v46, v250
	v_mul_f32_e32 v186, v47, v186
	v_mul_f32_e32 v192, v48, v192
	v_mul_f32_e32 v187, v49, v187
	v_cvt_pk_bf16_f32 v186, v250, v186
	v_cvt_pk_bf16_f32 v187, v192, v187
	global_store_dwordx4 v249, v[184:187], s[92:93]
	s_waitcnt vmcnt(15)
	v_lshlrev_b32_e32 v250, 16, v188
	v_and_b32_e32 v188, 0xffff0000, v188
	v_lshlrev_b32_e32 v192, 16, v189
	v_and_b32_e32 v189, 0xffff0000, v189
	v_max_f32_e32 v250, 0x0da24260, v250
	v_max_f32_e32 v188, 0x0da24260, v188
	v_max_f32_e32 v192, 0x0da24260, v192
	v_max_f32_e32 v189, 0x0da24260, v189
	v_mul_f32_e32 v250, v38, v250
	v_mul_f32_e32 v188, v39, v188
	v_mul_f32_e32 v192, v40, v192
	v_mul_f32_e32 v189, v41, v189
	v_cvt_pk_bf16_f32 v188, v250, v188
	v_cvt_pk_bf16_f32 v189, v192, v189
	v_lshlrev_b32_e32 v250, 16, v190
	v_and_b32_e32 v190, 0xffff0000, v190
	v_lshlrev_b32_e32 v192, 16, v191
	v_and_b32_e32 v191, 0xffff0000, v191
	v_max_f32_e32 v250, 0x0da24260, v250
	v_max_f32_e32 v190, 0x0da24260, v190
	v_max_f32_e32 v192, 0x0da24260, v192
	v_max_f32_e32 v191, 0x0da24260, v191
	v_mul_f32_e32 v250, v34, v250
	v_mul_f32_e32 v190, v35, v190
	v_mul_f32_e32 v192, v36, v192
	v_mul_f32_e32 v191, v37, v191
	v_cvt_pk_bf16_f32 v190, v250, v190
	v_cvt_pk_bf16_f32 v191, v192, v191
	global_store_dwordx4 v249, v[188:191], s[92:93] offset:256
	s_waitcnt vmcnt(15)
	v_lshlrev_b32_e32 v250, 16, v198
	v_and_b32_e32 v198, 0xffff0000, v198
	v_lshlrev_b32_e32 v192, 16, v199
	v_and_b32_e32 v199, 0xffff0000, v199
	v_max_f32_e32 v250, 0x0da24260, v250
	v_max_f32_e32 v198, 0x0da24260, v198
	v_max_f32_e32 v192, 0x0da24260, v192
	v_max_f32_e32 v199, 0x0da24260, v199
	v_mul_f32_e32 v250, v30, v250
	v_mul_f32_e32 v198, v31, v198
	v_mul_f32_e32 v192, v32, v192
	v_mul_f32_e32 v199, v33, v199
	v_cvt_pk_bf16_f32 v198, v250, v198
	v_cvt_pk_bf16_f32 v199, v192, v199
	v_lshlrev_b32_e32 v250, 16, v200
	v_and_b32_e32 v200, 0xffff0000, v200
	v_lshlrev_b32_e32 v192, 16, v201
	v_and_b32_e32 v201, 0xffff0000, v201
	v_max_f32_e32 v250, 0x0da24260, v250
	v_max_f32_e32 v200, 0x0da24260, v200
	v_max_f32_e32 v192, 0x0da24260, v192
	v_max_f32_e32 v201, 0x0da24260, v201
	v_mul_f32_e32 v250, v26, v250
	v_mul_f32_e32 v200, v27, v200
	v_mul_f32_e32 v192, v28, v192
	v_mul_f32_e32 v201, v29, v201
	v_cvt_pk_bf16_f32 v200, v250, v200
	v_cvt_pk_bf16_f32 v201, v192, v201
	global_store_dwordx4 v249, v[198:201], s[94:95]
	s_waitcnt vmcnt(15)
	v_lshlrev_b32_e32 v250, 16, v212
	v_and_b32_e32 v212, 0xffff0000, v212
	v_lshlrev_b32_e32 v192, 16, v213
	v_and_b32_e32 v213, 0xffff0000, v213
	v_max_f32_e32 v250, 0x0da24260, v250
	v_max_f32_e32 v212, 0x0da24260, v212
	v_max_f32_e32 v192, 0x0da24260, v192
	v_max_f32_e32 v213, 0x0da24260, v213
	v_mul_f32_e32 v250, v18, v250
	v_mul_f32_e32 v212, v19, v212
	v_mul_f32_e32 v192, v20, v192
	v_mul_f32_e32 v213, v21, v213
	v_cvt_pk_bf16_f32 v212, v250, v212
	v_cvt_pk_bf16_f32 v213, v192, v213
	v_lshlrev_b32_e32 v250, 16, v214
	v_and_b32_e32 v214, 0xffff0000, v214
	v_lshlrev_b32_e32 v192, 16, v215
	v_and_b32_e32 v215, 0xffff0000, v215
	v_max_f32_e32 v250, 0x0da24260, v250
	v_max_f32_e32 v214, 0x0da24260, v214
	v_max_f32_e32 v192, 0x0da24260, v192
	v_max_f32_e32 v215, 0x0da24260, v215
	v_mul_f32_e32 v250, v10, v250
	v_mul_f32_e32 v214, v11, v214
	v_mul_f32_e32 v192, v12, v192
	v_mul_f32_e32 v215, v13, v215
	v_cvt_pk_bf16_f32 v214, v250, v214
	v_cvt_pk_bf16_f32 v215, v192, v215
	global_store_dwordx4 v249, v[212:215], s[94:95] offset:256
	s_waitcnt vmcnt(15)
	v_lshlrev_b32_e32 v250, 16, v216
	v_and_b32_e32 v216, 0xffff0000, v216
	v_lshlrev_b32_e32 v192, 16, v217
	v_and_b32_e32 v217, 0xffff0000, v217
	v_max_f32_e32 v250, 0x0da24260, v250
	v_max_f32_e32 v216, 0x0da24260, v216
	v_max_f32_e32 v192, 0x0da24260, v192
	v_max_f32_e32 v217, 0x0da24260, v217
	v_mul_f32_e32 v250, v22, v250
	v_mul_f32_e32 v216, v23, v216
	v_mul_f32_e32 v192, v24, v192
	v_mul_f32_e32 v217, v25, v217
	v_cvt_pk_bf16_f32 v216, v250, v216
	v_cvt_pk_bf16_f32 v217, v192, v217
	v_lshlrev_b32_e32 v250, 16, v218
	v_and_b32_e32 v218, 0xffff0000, v218
	v_lshlrev_b32_e32 v192, 16, v219
	v_and_b32_e32 v219, 0xffff0000, v219
	v_max_f32_e32 v250, 0x0da24260, v250
	v_max_f32_e32 v218, 0x0da24260, v218
	v_max_f32_e32 v192, 0x0da24260, v192
	v_max_f32_e32 v219, 0x0da24260, v219
	v_mul_f32_e32 v250, v14, v250
	v_mul_f32_e32 v218, v15, v218
	v_mul_f32_e32 v192, v16, v192
	v_mul_f32_e32 v219, v17, v219
	v_cvt_pk_bf16_f32 v218, v250, v218
	v_cvt_pk_bf16_f32 v219, v192, v219
	global_store_dwordx4 v249, v[216:219], s[96:97]
	s_waitcnt vmcnt(15)
	v_lshlrev_b32_e32 v250, 16, v220
	v_and_b32_e32 v220, 0xffff0000, v220
	v_lshlrev_b32_e32 v192, 16, v221
	v_and_b32_e32 v221, 0xffff0000, v221
	v_max_f32_e32 v250, 0x0da24260, v250
	v_max_f32_e32 v220, 0x0da24260, v220
	v_max_f32_e32 v192, 0x0da24260, v192
	v_max_f32_e32 v221, 0x0da24260, v221
	v_mul_f32_e32 v250, v6, v250
	v_mul_f32_e32 v220, v7, v220
	v_mul_f32_e32 v192, v8, v192
	v_mul_f32_e32 v221, v9, v221
	v_cvt_pk_bf16_f32 v220, v250, v220
	v_cvt_pk_bf16_f32 v221, v192, v221
	v_lshlrev_b32_e32 v250, 16, v222
	v_and_b32_e32 v222, 0xffff0000, v222
	v_lshlrev_b32_e32 v192, 16, v223
	v_and_b32_e32 v223, 0xffff0000, v223
	v_max_f32_e32 v250, 0x0da24260, v250
	v_max_f32_e32 v222, 0x0da24260, v222
	v_max_f32_e32 v192, 0x0da24260, v192
	v_max_f32_e32 v223, 0x0da24260, v223
	v_mul_f32_e32 v250, v2, v250
	v_mul_f32_e32 v222, v3, v222
	v_mul_f32_e32 v192, v4, v192
	v_mul_f32_e32 v223, v5, v223
	v_cvt_pk_bf16_f32 v222, v250, v222
	v_cvt_pk_bf16_f32 v223, v192, v223
	global_store_dwordx4 v249, v[220:223], s[96:97] offset:256
